# speedup vs baseline: 1.0030x; 1.0030x over previous
;   __device__ __forceinline__ void operator()(int m, int n, f32x4 v) const {
;     float r = srstd[m - m0];
;     v[0] *= r; v[1] *= r; v[2] *= r; v[3] *= r;
;     int h = n / 192, hc = n - h * 192;
;     if (hc >= 128 && m < TX) v = rope4(v, rope, m & 2047, (hc - 128) >> 1);
;     store4bf(Q + (size_t)m * 768 + n, v);
.LBB0_1403:
	s_or_b64 exec, exec, s[0:1]
	v_lshlrev_b32_e32 v130, 6, v131
	v_or_b32_e32 v131, s50, v133
	v_add_u32_e32 v136, v131, v130
	v_lshlrev_b32_e32 v0, 5, v0
	v_lshlrev_b32_e32 v131, 2, v132
	v_subrev_u32_e32 v130, s50, v136
	v_lshl_add_u32 v130, v130, 2, v201
	v_or3_b32 v139, v0, v131, s15
	v_and_b32_e32 v224, 63, v139
	v_lshlrev_b32_e32 v224, 2, v224
	v_mov_b32_e32 v225, v136
	v_and_b32_e32 v225, 0x7ff, v225
	v_lshl_or_b32 v225, v225, 8, v224
	global_load_dwordx4 v[148:151], v225, s[40:41]
	global_load_dwordx4 v[152:155], v225, s[40:41] offset:64
	v_add_u32_e32 v225, 16, v136
	v_and_b32_e32 v225, 0x7ff, v225
	v_lshl_or_b32 v225, v225, 8, v224
	global_load_dwordx4 v[156:159], v225, s[40:41]
	global_load_dwordx4 v[160:163], v225, s[40:41] offset:64
	v_add_u32_e32 v225, 32, v136
	v_and_b32_e32 v225, 0x7ff, v225
	v_lshl_or_b32 v225, v225, 8, v224
	global_load_dwordx4 v[164:167], v225, s[40:41]
	global_load_dwordx4 v[168:171], v225, s[40:41] offset:64
	v_add_u32_e32 v225, 48, v136
	v_and_b32_e32 v225, 0x7ff, v225
	v_lshl_or_b32 v225, v225, 8, v224
	global_load_dwordx4 v[172:175], v225, s[40:41]
	global_load_dwordx4 v[176:179], v225, s[40:41] offset:64
	v_add_u32_e32 v225, 128, v136
	v_and_b32_e32 v225, 0x7ff, v225
	v_lshl_or_b32 v225, v225, 8, v224
	global_load_dwordx4 v[180:183], v225, s[40:41]
	global_load_dwordx4 v[184:187], v225, s[40:41] offset:64
	v_add_u32_e32 v225, 144, v136
	v_and_b32_e32 v225, 0x7ff, v225
	v_lshl_or_b32 v225, v225, 8, v224
	global_load_dwordx4 v[188:191], v225, s[40:41]
	global_load_dwordx4 v[192:195], v225, s[40:41] offset:64
	v_add_u32_e32 v225, 160, v136
	v_and_b32_e32 v225, 0x7ff, v225
	v_lshl_or_b32 v225, v225, 8, v224
	global_load_dwordx4 v[208:211], v225, s[40:41]
	global_load_dwordx4 v[212:215], v225, s[40:41] offset:64
	v_add_u32_e32 v225, 176, v136
	v_and_b32_e32 v225, 0x7ff, v225
	v_lshl_or_b32 v225, v225, 8, v224
	global_load_dwordx4 v[216:219], v225, s[40:41]
	global_load_dwordx4 v[220:223], v225, s[40:41] offset:64
	s_waitcnt vmcnt(0)
	v_lshlrev_b32_e32 v0, 5, v136
	ds_read_b32 v130, v130
	v_and_b32_e32 v138, 0xf9e0, v0
	v_mul_u32_u24_e32 v0, 0x2aab, v139
	v_lshrrev_b32_e32 v0, 21, v0
	v_mul_lo_u16_e32 v0, 0xc0, v0
	v_sub_u16_e32 v0, v139, v0
	s_movk_i32 s0, 0x7f
	v_cmp_gt_i32_e64 s[12:13], s74, v136
	v_cmp_lt_u16_e32 vcc, s0, v0
	v_add_u16_e32 v0, 0xff80, v0
	s_waitcnt lgkmcnt(0)
	v_pk_mul_f32 v[132:133], v[126:127], v[130:131] op_sel_hi:[1,0]
	v_pk_mul_f32 v[128:129], v[128:129], v[130:131] op_sel_hi:[1,0]
	s_and_b64 s[6:7], s[12:13], vcc
	v_lshrrev_b16_e32 v137, 1, v0
	s_and_saveexec_b64 s[0:1], s[6:7]
	s_cbranch_execz .LBB0_1405
	v_add_lshl_u32 v0, v138, v137, 3
	v_mov_b32_e32 v140, v148
	v_mov_b32_e32 v141, v149
	v_mov_b32_e32 v142, v150
	v_mov_b32_e32 v143, v151
	v_pk_mul_f32 v[144:145], v[132:133], v[140:141] op_sel:[1,1] op_sel_hi:[1,0]
	v_mul_f32_e32 v0, v129, v143
	v_pk_mul_f32 v[126:127], v[132:133], v[140:141]
	v_pk_fma_f32 v[132:133], v[132:133], v[140:141], v[144:145] op_sel_hi:[0,1,1]
	v_pk_fma_f32 v[140:141], v[128:129], v[142:143], v[0:1] op_sel_hi:[1,1,0] neg_lo:[0,0,1] neg_hi:[0,0,1]
	v_mul_f32_e32 v0, v128, v143
	v_pk_fma_f32 v[142:143], v[128:129], v[142:143], v[0:1] op_sel:[1,0,0] op_sel_hi:[0,1,0]
	v_sub_f32_e32 v132, v126, v144
	v_mov_b32_e32 v128, v140
	v_mov_b32_e32 v129, v142
.LBB0_1405:
	s_or_b64 exec, exec, s[0:1]
	v_cvt_pk_bf16_f32 v132, v132, v133
	v_cvt_pk_bf16_f32 v133, v128, v129
	v_or_b32_e32 v128, 16, v139
	v_mul_u32_u24_e32 v129, 0x2aab, v128
	v_mov_b64_e32 v[126:127], s[94:95]
	s_movk_i32 s0, 0x600
	v_lshrrev_b32_e32 v129, 21, v129
	v_mad_i64_i32 v[126:127], s[0:1], v136, s0, v[126:127]
	v_mul_lo_u16_e32 v129, 0xc0, v129
	v_sub_u16_e32 v128, v128, v129
	s_movk_i32 s0, 0x7f
	v_mov_b32_e32 v131, v130
	v_lshlrev_b32_e32 v0, 1, v139
	v_cmp_lt_u16_e64 s[6:7], s0, v128
	v_add_u16_e32 v128, 0xff80, v128
	v_lshl_add_u64 v[126:127], v[126:127], 0, v[0:1]
	v_pk_mul_f32 v[122:123], v[122:123], v[130:131]
	v_pk_mul_f32 v[124:125], v[124:125], v[130:131]
	s_and_b64 s[8:9], s[12:13], s[6:7]
	v_lshrrev_b16_e32 v128, 1, v128
	global_store_dwordx2 v[126:127], v[132:133], off
	s_and_saveexec_b64 s[0:1], s[8:9]
	s_cbranch_execz .LBB0_1407
	v_add_lshl_u32 v129, v138, v128, 3
	v_mov_b32_e32 v140, v152
	v_mov_b32_e32 v141, v153
	v_mov_b32_e32 v142, v154
	v_mov_b32_e32 v143, v155
	v_pk_mul_f32 v[144:145], v[122:123], v[140:141] op_sel:[1,1] op_sel_hi:[1,0]
	v_pk_mul_f32 v[132:133], v[122:123], v[140:141]
	v_pk_fma_f32 v[122:123], v[122:123], v[140:141], v[144:145] op_sel_hi:[0,1,1]
	v_mul_f32_e32 v122, v125, v143
	v_pk_fma_f32 v[140:141], v[124:125], v[142:143], v[122:123] op_sel_hi:[1,1,0] neg_lo:[0,0,1] neg_hi:[0,0,1]
	v_mul_f32_e32 v122, v124, v143
	v_pk_fma_f32 v[142:143], v[124:125], v[142:143], v[122:123] op_sel:[1,0,0] op_sel_hi:[0,1,0]
	v_sub_f32_e32 v122, v132, v144
	v_mov_b32_e32 v124, v140
	v_mov_b32_e32 v125, v142
.LBB0_1407:
	s_or_b64 exec, exec, s[0:1]
	v_or_b32_e32 v132, 16, v136
	v_cvt_pk_bf16_f32 v140, v122, v123
	v_subrev_u32_e32 v122, s50, v132
	v_lshl_add_u32 v122, v122, 2, v201
	ds_read_b32 v122, v122
	v_cmp_gt_i32_e64 s[14:15], s74, v132
	v_lshlrev_b32_e32 v123, 5, v132
	v_cvt_pk_bf16_f32 v141, v124, v125
	v_and_b32_e32 v129, 0xfbe0, v123
	s_waitcnt lgkmcnt(0)
	v_pk_mul_f32 v[124:125], v[118:119], v[122:123] op_sel_hi:[1,0]
	v_pk_mul_f32 v[120:121], v[120:121], v[122:123] op_sel_hi:[1,0]
	s_and_b64 s[8:9], s[14:15], vcc
	global_store_dwordx2 v[126:127], v[140:141], off offset:32
	s_and_saveexec_b64 s[0:1], s[8:9]
	s_cbranch_execz .LBB0_1409
	v_add_lshl_u32 v118, v129, v137, 3
	v_mov_b32_e32 v140, v156
	v_mov_b32_e32 v141, v157
	v_mov_b32_e32 v142, v158
	v_mov_b32_e32 v143, v159
	v_pk_mul_f32 v[144:145], v[124:125], v[140:141] op_sel:[1,1] op_sel_hi:[1,0]
	v_pk_mul_f32 v[118:119], v[124:125], v[140:141]
	v_pk_fma_f32 v[124:125], v[124:125], v[140:141], v[144:145] op_sel_hi:[0,1,1]
	v_mul_f32_e32 v124, v121, v143
	v_pk_fma_f32 v[140:141], v[120:121], v[142:143], v[124:125] op_sel_hi:[1,1,0] neg_lo:[0,0,1] neg_hi:[0,0,1]
	v_mul_f32_e32 v124, v120, v143
	v_pk_fma_f32 v[142:143], v[120:121], v[142:143], v[124:125] op_sel:[1,0,0] op_sel_hi:[0,1,0]
	v_sub_f32_e32 v124, v118, v144
	v_mov_b32_e32 v120, v140
	v_mov_b32_e32 v121, v142
;   __device__ __forceinline__ void operator()(int m, int n, f32x4 v) const {
;     float r = srstd[m - m0];
;     v[0] *= r; v[1] *= r; v[2] *= r; v[3] *= r;
;     int h = n / 192, hc = n - h * 192;
;     if (hc >= 128 && m < TX) v = rope4(v, rope, m & 2047, (hc - 128) >> 1);
;     store4bf(Q + (size_t)m * 768 + n, v);
.LBB0_1409:
	s_or_b64 exec, exec, s[0:1]
	v_mov_b64_e32 v[118:119], s[94:95]
	s_movk_i32 s0, 0x600
	v_mov_b32_e32 v123, v122
	v_mad_i64_i32 v[118:119], s[0:1], v132, s0, v[118:119]
	v_lshl_add_u64 v[118:119], v[118:119], 0, v[0:1]
	v_cvt_pk_bf16_f32 v124, v124, v125
	v_cvt_pk_bf16_f32 v125, v120, v121
	v_pk_mul_f32 v[114:115], v[114:115], v[122:123]
	v_pk_mul_f32 v[116:117], v[116:117], v[122:123]
	s_and_b64 s[8:9], s[14:15], s[6:7]
	global_store_dwordx2 v[118:119], v[124:125], off
	s_and_saveexec_b64 s[0:1], s[8:9]
	s_cbranch_execz .LBB0_1411
	v_add_lshl_u32 v120, v129, v128, 3
	v_mov_b32_e32 v140, v160
	v_mov_b32_e32 v141, v161
	v_mov_b32_e32 v142, v162
	v_mov_b32_e32 v143, v163
	v_pk_mul_f32 v[124:125], v[114:115], v[140:141] op_sel:[1,1] op_sel_hi:[1,0]
	v_pk_mul_f32 v[120:121], v[114:115], v[140:141]
	v_pk_fma_f32 v[114:115], v[114:115], v[140:141], v[124:125] op_sel_hi:[0,1,1]
	v_mul_f32_e32 v114, v117, v143
	v_pk_fma_f32 v[132:133], v[116:117], v[142:143], v[114:115] op_sel_hi:[1,1,0] neg_lo:[0,0,1] neg_hi:[0,0,1]
	v_mul_f32_e32 v114, v116, v143
	v_pk_fma_f32 v[140:141], v[116:117], v[142:143], v[114:115] op_sel:[1,0,0] op_sel_hi:[0,1,0]
	v_sub_f32_e32 v114, v120, v124
	v_mov_b32_e32 v116, v132
	v_mov_b32_e32 v117, v140
.LBB0_1411:
	s_or_b64 exec, exec, s[0:1]
	v_or_b32_e32 v121, 32, v136
	v_cvt_pk_bf16_f32 v124, v114, v115
	v_subrev_u32_e32 v114, s50, v121
	v_lshl_add_u32 v114, v114, 2, v201
	ds_read_b32 v114, v114
	v_cmp_gt_i32_e64 s[16:17], s74, v121
	v_lshlrev_b32_e32 v115, 5, v121
	v_cvt_pk_bf16_f32 v125, v116, v117
	v_and_b32_e32 v120, 0xfde0, v115
	s_waitcnt lgkmcnt(0)
	v_pk_mul_f32 v[116:117], v[110:111], v[114:115] op_sel_hi:[1,0]
	v_pk_mul_f32 v[112:113], v[112:113], v[114:115] op_sel_hi:[1,0]
	s_and_b64 s[8:9], s[16:17], vcc
	global_store_dwordx2 v[118:119], v[124:125], off offset:32
	s_and_saveexec_b64 s[0:1], s[8:9]
	s_cbranch_execz .LBB0_1413
	v_add_lshl_u32 v110, v120, v137, 3
	v_mov_b32_e32 v140, v164
	v_mov_b32_e32 v141, v165
	v_mov_b32_e32 v142, v166
	v_mov_b32_e32 v143, v167
	v_pk_mul_f32 v[124:125], v[116:117], v[140:141] op_sel:[1,1] op_sel_hi:[1,0]
	v_pk_mul_f32 v[110:111], v[116:117], v[140:141]
	v_pk_fma_f32 v[116:117], v[116:117], v[140:141], v[124:125] op_sel_hi:[0,1,1]
	v_mul_f32_e32 v116, v113, v143
	v_pk_fma_f32 v[132:133], v[112:113], v[142:143], v[116:117] op_sel_hi:[1,1,0] neg_lo:[0,0,1] neg_hi:[0,0,1]
	v_mul_f32_e32 v116, v112, v143
	v_pk_fma_f32 v[140:141], v[112:113], v[142:143], v[116:117] op_sel:[1,0,0] op_sel_hi:[0,1,0]
	v_sub_f32_e32 v116, v110, v124
	v_mov_b32_e32 v112, v132
	v_mov_b32_e32 v113, v140
.LBB0_1413:
	s_or_b64 exec, exec, s[0:1]
	v_mov_b64_e32 v[110:111], s[94:95]
	s_movk_i32 s0, 0x600
	v_mov_b32_e32 v115, v114
	v_mad_i64_i32 v[110:111], s[0:1], v121, s0, v[110:111]
	v_lshl_add_u64 v[110:111], v[110:111], 0, v[0:1]
	v_cvt_pk_bf16_f32 v116, v116, v117
	v_cvt_pk_bf16_f32 v117, v112, v113
	v_pk_mul_f32 v[106:107], v[106:107], v[114:115]
	v_pk_mul_f32 v[108:109], v[108:109], v[114:115]
	s_and_b64 s[8:9], s[16:17], s[6:7]
	global_store_dwordx2 v[110:111], v[116:117], off
	s_and_saveexec_b64 s[0:1], s[8:9]
	s_cbranch_execz .LBB0_1415
	v_add_lshl_u32 v112, v120, v128, 3
	v_mov_b32_e32 v140, v168
	v_mov_b32_e32 v141, v169
	v_mov_b32_e32 v142, v170
	v_mov_b32_e32 v143, v171
	v_pk_mul_f32 v[116:117], v[106:107], v[140:141] op_sel:[1,1] op_sel_hi:[1,0]
	v_pk_mul_f32 v[112:113], v[106:107], v[140:141]
	v_pk_fma_f32 v[106:107], v[106:107], v[140:141], v[116:117] op_sel_hi:[0,1,1]
	v_mul_f32_e32 v106, v109, v143
	v_pk_fma_f32 v[124:125], v[108:109], v[142:143], v[106:107] op_sel_hi:[1,1,0] neg_lo:[0,0,1] neg_hi:[0,0,1]
	v_mul_f32_e32 v106, v108, v143
	v_pk_fma_f32 v[132:133], v[108:109], v[142:143], v[106:107] op_sel:[1,0,0] op_sel_hi:[0,1,0]
	v_sub_f32_e32 v106, v112, v116
	v_mov_b32_e32 v108, v124
	v_mov_b32_e32 v109, v132
.LBB0_1415:
	s_or_b64 exec, exec, s[0:1]
	v_or_b32_e32 v113, 48, v136
	v_cvt_pk_bf16_f32 v116, v106, v107
	v_subrev_u32_e32 v106, s50, v113
	v_lshl_add_u32 v106, v106, 2, v201
	ds_read_b32 v106, v106
	v_cmp_gt_i32_e64 s[18:19], s74, v113
	v_lshlrev_b32_e32 v107, 5, v113
	v_cvt_pk_bf16_f32 v117, v108, v109
	v_and_b32_e32 v112, 0xffe0, v107
	s_waitcnt lgkmcnt(0)
	v_pk_mul_f32 v[108:109], v[102:103], v[106:107] op_sel_hi:[1,0]
	v_pk_mul_f32 v[104:105], v[104:105], v[106:107] op_sel_hi:[1,0]
	s_and_b64 s[8:9], s[18:19], vcc
	global_store_dwordx2 v[110:111], v[116:117], off offset:32
	s_and_saveexec_b64 s[0:1], s[8:9]
	s_cbranch_execz .LBB0_1417
	v_add_lshl_u32 v102, v112, v137, 3
	v_mov_b32_e32 v140, v172
	v_mov_b32_e32 v141, v173
	v_mov_b32_e32 v142, v174
	v_mov_b32_e32 v143, v175
	v_pk_mul_f32 v[116:117], v[108:109], v[140:141] op_sel:[1,1] op_sel_hi:[1,0]
	v_pk_mul_f32 v[102:103], v[108:109], v[140:141]
	v_pk_fma_f32 v[108:109], v[108:109], v[140:141], v[116:117] op_sel_hi:[0,1,1]
	v_mul_f32_e32 v108, v105, v143
	v_pk_fma_f32 v[124:125], v[104:105], v[142:143], v[108:109] op_sel_hi:[1,1,0] neg_lo:[0,0,1] neg_hi:[0,0,1]
	v_mul_f32_e32 v108, v104, v143
	v_pk_fma_f32 v[132:133], v[104:105], v[142:143], v[108:109] op_sel:[1,0,0] op_sel_hi:[0,1,0]
	v_sub_f32_e32 v108, v102, v116
	v_mov_b32_e32 v104, v124
	v_mov_b32_e32 v105, v132
;   __device__ __forceinline__ void operator()(int m, int n, f32x4 v) const {
;     float r = srstd[m - m0];
;     v[0] *= r; v[1] *= r; v[2] *= r; v[3] *= r;
;     int h = n / 192, hc = n - h * 192;
;     if (hc >= 128 && m < TX) v = rope4(v, rope, m & 2047, (hc - 128) >> 1);
;     store4bf(Q + (size_t)m * 768 + n, v);
;   }
.LBB0_1417:
	s_or_b64 exec, exec, s[0:1]
	v_mov_b64_e32 v[102:103], s[94:95]
	s_movk_i32 s0, 0x600
	v_mov_b32_e32 v107, v106
	v_mad_i64_i32 v[102:103], s[0:1], v113, s0, v[102:103]
	v_lshl_add_u64 v[102:103], v[102:103], 0, v[0:1]
	v_cvt_pk_bf16_f32 v108, v108, v109
	v_cvt_pk_bf16_f32 v109, v104, v105
	v_pk_mul_f32 v[98:99], v[98:99], v[106:107]
	v_pk_mul_f32 v[100:101], v[100:101], v[106:107]
	s_and_b64 s[8:9], s[18:19], s[6:7]
	global_store_dwordx2 v[102:103], v[108:109], off
	s_and_saveexec_b64 s[0:1], s[8:9]
	s_cbranch_execz .LBB0_1419
	v_add_lshl_u32 v104, v112, v128, 3
	v_mov_b32_e32 v140, v176
	v_mov_b32_e32 v141, v177
	v_mov_b32_e32 v142, v178
	v_mov_b32_e32 v143, v179
	v_pk_mul_f32 v[108:109], v[98:99], v[140:141] op_sel:[1,1] op_sel_hi:[1,0]
	v_pk_mul_f32 v[104:105], v[98:99], v[140:141]
	v_pk_fma_f32 v[98:99], v[98:99], v[140:141], v[108:109] op_sel_hi:[0,1,1]
	v_mul_f32_e32 v98, v101, v143
	v_pk_fma_f32 v[116:117], v[100:101], v[142:143], v[98:99] op_sel_hi:[1,1,0] neg_lo:[0,0,1] neg_hi:[0,0,1]
	v_mul_f32_e32 v98, v100, v143
	v_pk_fma_f32 v[124:125], v[100:101], v[142:143], v[98:99] op_sel:[1,0,0] op_sel_hi:[0,1,0]
	v_sub_f32_e32 v98, v104, v108
	v_mov_b32_e32 v100, v116
	v_mov_b32_e32 v101, v124
.LBB0_1419:
	s_or_b64 exec, exec, s[0:1]
	v_cvt_pk_bf16_f32 v98, v98, v99
	v_cvt_pk_bf16_f32 v99, v100, v101
	global_store_dwordx2 v[102:103], v[98:99], off offset:32
	v_or_b32_e32 v98, 0x80, v139
	v_mul_u32_u24_e32 v99, 0x2aab, v98
	v_lshrrev_b32_e32 v99, 21, v99
	v_mul_lo_u16_e32 v99, 0xc0, v99
	v_sub_u16_e32 v98, v98, v99
	s_movk_i32 s0, 0x7f
	v_cmp_lt_u16_e64 s[8:9], s0, v98
	v_add_u16_e32 v98, 0xff80, v98
	v_pk_mul_f32 v[94:95], v[94:95], v[130:131]
	v_pk_mul_f32 v[96:97], v[96:97], v[130:131]
	s_and_b64 s[10:11], s[12:13], s[8:9]
	v_lshrrev_b16_e32 v98, 1, v98
	s_and_saveexec_b64 s[0:1], s[10:11]
	s_cbranch_execz .LBB0_1421
	v_add_lshl_u32 v99, v138, v98, 3
	v_mov_b32_e32 v140, v148
	v_mov_b32_e32 v141, v149
	v_mov_b32_e32 v142, v150
	v_mov_b32_e32 v143, v151
	v_pk_mul_f32 v[104:105], v[94:95], v[140:141] op_sel:[1,1] op_sel_hi:[1,0]
	v_pk_mul_f32 v[100:101], v[94:95], v[140:141]
	v_pk_fma_f32 v[94:95], v[94:95], v[140:141], v[104:105] op_sel_hi:[0,1,1]
	v_mul_f32_e32 v94, v97, v143
	v_pk_fma_f32 v[108:109], v[96:97], v[142:143], v[94:95] op_sel_hi:[1,1,0] neg_lo:[0,0,1] neg_hi:[0,0,1]
	v_mul_f32_e32 v94, v96, v143
	v_pk_fma_f32 v[116:117], v[96:97], v[142:143], v[94:95] op_sel:[1,0,0] op_sel_hi:[0,1,0]
	v_sub_f32_e32 v94, v100, v104
	v_mov_b32_e32 v96, v108
	v_mov_b32_e32 v97, v116
.LBB0_1421:
	s_or_b64 exec, exec, s[0:1]
	v_cvt_pk_bf16_f32 v94, v94, v95
	v_cvt_pk_bf16_f32 v95, v96, v97
	global_store_dwordx2 v[126:127], v[94:95], off offset:256
	v_or_b32_e32 v94, 0x90, v139
	v_mul_u32_u24_e32 v95, 0x2aab, v94
	v_lshrrev_b32_e32 v95, 21, v95
	v_mul_lo_u16_e32 v95, 0xc0, v95
	v_sub_u16_e32 v94, v94, v95
	s_movk_i32 s0, 0x7f
	v_cmp_lt_u16_e64 s[10:11], s0, v94
	v_add_u16_e32 v94, 0xff80, v94
	v_pk_mul_f32 v[90:91], v[90:91], v[130:131]
	v_pk_mul_f32 v[92:93], v[92:93], v[130:131]
	s_and_b64 s[12:13], s[12:13], s[10:11]
	v_lshrrev_b16_e32 v94, 1, v94
	s_and_saveexec_b64 s[0:1], s[12:13]
	s_cbranch_execz .LBB0_1423
	v_add_lshl_u32 v95, v138, v94, 3
	v_mov_b32_e32 v130, v152
	v_mov_b32_e32 v131, v153
	v_mov_b32_e32 v132, v154
	v_mov_b32_e32 v133, v155
	v_pk_mul_f32 v[100:101], v[90:91], v[130:131] op_sel:[1,1] op_sel_hi:[1,0]
	v_pk_mul_f32 v[96:97], v[90:91], v[130:131]
	v_pk_fma_f32 v[90:91], v[90:91], v[130:131], v[100:101] op_sel_hi:[0,1,1]
	v_mul_f32_e32 v90, v93, v133
	v_pk_fma_f32 v[104:105], v[92:93], v[132:133], v[90:91] op_sel_hi:[1,1,0] neg_lo:[0,0,1] neg_hi:[0,0,1]
	v_mul_f32_e32 v90, v92, v133
	v_pk_fma_f32 v[108:109], v[92:93], v[132:133], v[90:91] op_sel:[1,0,0] op_sel_hi:[0,1,0]
	v_sub_f32_e32 v90, v96, v100
	v_mov_b32_e32 v92, v104
	v_mov_b32_e32 v93, v108
.LBB0_1423:
	s_or_b64 exec, exec, s[0:1]
	v_cvt_pk_bf16_f32 v90, v90, v91
	v_cvt_pk_bf16_f32 v91, v92, v93
	v_pk_mul_f32 v[86:87], v[86:87], v[122:123]
	v_pk_mul_f32 v[88:89], v[88:89], v[122:123]
	s_and_b64 s[12:13], s[14:15], s[8:9]
	global_store_dwordx2 v[126:127], v[90:91], off offset:288
	s_and_saveexec_b64 s[0:1], s[12:13]
	s_cbranch_execz .LBB0_1425
	v_add_lshl_u32 v90, v129, v98, 3
	v_mov_b32_e32 v90, v156
	v_mov_b32_e32 v91, v157
	v_mov_b32_e32 v92, v158
	v_mov_b32_e32 v93, v159
	v_pk_mul_f32 v[100:101], v[86:87], v[90:91] op_sel:[1,1] op_sel_hi:[1,0]
	v_pk_mul_f32 v[96:97], v[86:87], v[90:91]
	v_pk_fma_f32 v[86:87], v[86:87], v[90:91], v[100:101] op_sel_hi:[0,1,1]
	v_mul_f32_e32 v86, v89, v93
	v_pk_fma_f32 v[90:91], v[88:89], v[92:93], v[86:87] op_sel_hi:[1,1,0] neg_lo:[0,0,1] neg_hi:[0,0,1]
	v_mul_f32_e32 v86, v88, v93
	v_pk_fma_f32 v[92:93], v[88:89], v[92:93], v[86:87] op_sel:[1,0,0] op_sel_hi:[0,1,0]
	v_sub_f32_e32 v86, v96, v100
	v_mov_b32_e32 v88, v90
	v_mov_b32_e32 v89, v92
.LBB0_1425:
	s_or_b64 exec, exec, s[0:1]
	v_cvt_pk_bf16_f32 v86, v86, v87
	v_cvt_pk_bf16_f32 v87, v88, v89
	v_pk_mul_f32 v[82:83], v[82:83], v[122:123]
	v_pk_mul_f32 v[84:85], v[84:85], v[122:123]
	s_and_b64 s[12:13], s[14:15], s[10:11]
	global_store_dwordx2 v[118:119], v[86:87], off offset:256
	s_and_saveexec_b64 s[0:1], s[12:13]
	s_cbranch_execz .LBB0_1427
	v_add_lshl_u32 v86, v129, v94, 3
	v_mov_b32_e32 v86, v160
	v_mov_b32_e32 v87, v161
	v_mov_b32_e32 v88, v162
	v_mov_b32_e32 v89, v163
	v_pk_mul_f32 v[92:93], v[82:83], v[86:87] op_sel:[1,1] op_sel_hi:[1,0]
	v_pk_mul_f32 v[90:91], v[82:83], v[86:87]
	v_pk_fma_f32 v[82:83], v[82:83], v[86:87], v[92:93] op_sel_hi:[0,1,1]
	v_mul_f32_e32 v82, v85, v89
	v_pk_fma_f32 v[86:87], v[84:85], v[88:89], v[82:83] op_sel_hi:[1,1,0] neg_lo:[0,0,1] neg_hi:[0,0,1]
	v_mul_f32_e32 v82, v84, v89
	v_pk_fma_f32 v[88:89], v[84:85], v[88:89], v[82:83] op_sel:[1,0,0] op_sel_hi:[0,1,0]
	v_sub_f32_e32 v82, v90, v92
	v_mov_b32_e32 v84, v86
	v_mov_b32_e32 v85, v88
;   __device__ __forceinline__ void operator()(int m, int n, f32x4 v) const {
;     float r = srstd[m - m0];
;     v[0] *= r; v[1] *= r; v[2] *= r; v[3] *= r;
;     int h = n / 192, hc = n - h * 192;
;     if (hc >= 128 && m < TX) v = rope4(v, rope, m & 2047, (hc - 128) >> 1);
;     store4bf(Q + (size_t)m * 768 + n, v);
;   }
.LBB0_1427:
	s_or_b64 exec, exec, s[0:1]
	v_cvt_pk_bf16_f32 v82, v82, v83
	v_cvt_pk_bf16_f32 v83, v84, v85
	v_pk_mul_f32 v[78:79], v[78:79], v[114:115]
	v_pk_mul_f32 v[80:81], v[80:81], v[114:115]
	s_and_b64 s[12:13], s[16:17], s[8:9]
	global_store_dwordx2 v[118:119], v[82:83], off offset:288
	s_and_saveexec_b64 s[0:1], s[12:13]
	s_cbranch_execz .LBB0_1429
	v_add_lshl_u32 v82, v120, v98, 3
	v_mov_b32_e32 v82, v164
	v_mov_b32_e32 v83, v165
	v_mov_b32_e32 v84, v166
	v_mov_b32_e32 v85, v167
	v_pk_mul_f32 v[88:89], v[78:79], v[82:83] op_sel:[1,1] op_sel_hi:[1,0]
	v_pk_mul_f32 v[86:87], v[78:79], v[82:83]
	v_pk_fma_f32 v[78:79], v[78:79], v[82:83], v[88:89] op_sel_hi:[0,1,1]
	v_mul_f32_e32 v78, v81, v85
	v_pk_fma_f32 v[82:83], v[80:81], v[84:85], v[78:79] op_sel_hi:[1,1,0] neg_lo:[0,0,1] neg_hi:[0,0,1]
	v_mul_f32_e32 v78, v80, v85
	v_pk_fma_f32 v[84:85], v[80:81], v[84:85], v[78:79] op_sel:[1,0,0] op_sel_hi:[0,1,0]
	v_sub_f32_e32 v78, v86, v88
	v_mov_b32_e32 v80, v82
	v_mov_b32_e32 v81, v84
.LBB0_1429:
	s_or_b64 exec, exec, s[0:1]
	v_cvt_pk_bf16_f32 v78, v78, v79
	v_cvt_pk_bf16_f32 v79, v80, v81
	v_pk_mul_f32 v[74:75], v[74:75], v[114:115]
	v_pk_mul_f32 v[76:77], v[76:77], v[114:115]
	s_and_b64 s[12:13], s[16:17], s[10:11]
	global_store_dwordx2 v[110:111], v[78:79], off offset:256
	s_and_saveexec_b64 s[0:1], s[12:13]
	s_cbranch_execz .LBB0_1431
	v_add_lshl_u32 v78, v120, v94, 3
	v_mov_b32_e32 v78, v168
	v_mov_b32_e32 v79, v169
	v_mov_b32_e32 v80, v170
	v_mov_b32_e32 v81, v171
	v_pk_mul_f32 v[84:85], v[74:75], v[78:79] op_sel:[1,1] op_sel_hi:[1,0]
	v_pk_mul_f32 v[82:83], v[74:75], v[78:79]
	v_pk_fma_f32 v[74:75], v[74:75], v[78:79], v[84:85] op_sel_hi:[0,1,1]
	v_mul_f32_e32 v74, v77, v81
	v_pk_fma_f32 v[78:79], v[76:77], v[80:81], v[74:75] op_sel_hi:[1,1,0] neg_lo:[0,0,1] neg_hi:[0,0,1]
	v_mul_f32_e32 v74, v76, v81
	v_pk_fma_f32 v[80:81], v[76:77], v[80:81], v[74:75] op_sel:[1,0,0] op_sel_hi:[0,1,0]
	v_sub_f32_e32 v74, v82, v84
	v_mov_b32_e32 v76, v78
	v_mov_b32_e32 v77, v80
.LBB0_1431:
	s_or_b64 exec, exec, s[0:1]
	v_cvt_pk_bf16_f32 v74, v74, v75
	v_cvt_pk_bf16_f32 v75, v76, v77
	v_pk_mul_f32 v[70:71], v[70:71], v[106:107]
	v_pk_mul_f32 v[72:73], v[72:73], v[106:107]
	s_and_b64 s[12:13], s[18:19], s[8:9]
	global_store_dwordx2 v[110:111], v[74:75], off offset:288
	s_and_saveexec_b64 s[0:1], s[12:13]
	s_cbranch_execz .LBB0_1433
	v_add_lshl_u32 v74, v112, v98, 3
	v_mov_b32_e32 v74, v172
	v_mov_b32_e32 v75, v173
	v_mov_b32_e32 v76, v174
	v_mov_b32_e32 v77, v175
	v_pk_mul_f32 v[80:81], v[70:71], v[74:75] op_sel:[1,1] op_sel_hi:[1,0]
	v_pk_mul_f32 v[78:79], v[70:71], v[74:75]
	v_pk_fma_f32 v[70:71], v[70:71], v[74:75], v[80:81] op_sel_hi:[0,1,1]
	v_mul_f32_e32 v70, v73, v77
	v_pk_fma_f32 v[74:75], v[72:73], v[76:77], v[70:71] op_sel_hi:[1,1,0] neg_lo:[0,0,1] neg_hi:[0,0,1]
	v_mul_f32_e32 v70, v72, v77
	v_pk_fma_f32 v[76:77], v[72:73], v[76:77], v[70:71] op_sel:[1,0,0] op_sel_hi:[0,1,0]
	v_sub_f32_e32 v70, v78, v80
	v_mov_b32_e32 v72, v74
	v_mov_b32_e32 v73, v76
.LBB0_1433:
	s_or_b64 exec, exec, s[0:1]
	v_cvt_pk_bf16_f32 v70, v70, v71
	v_cvt_pk_bf16_f32 v71, v72, v73
	v_pk_mul_f32 v[66:67], v[66:67], v[106:107]
	v_pk_mul_f32 v[68:69], v[68:69], v[106:107]
	s_and_b64 s[12:13], s[18:19], s[10:11]
	global_store_dwordx2 v[102:103], v[70:71], off offset:256
	s_and_saveexec_b64 s[0:1], s[12:13]
	s_cbranch_execz .LBB0_1435
	v_add_lshl_u32 v70, v112, v94, 3
	v_mov_b32_e32 v70, v176
	v_mov_b32_e32 v71, v177
	v_mov_b32_e32 v72, v178
	v_mov_b32_e32 v73, v179
	v_pk_mul_f32 v[76:77], v[66:67], v[70:71] op_sel:[1,1] op_sel_hi:[1,0]
	v_pk_mul_f32 v[74:75], v[66:67], v[70:71]
	v_pk_fma_f32 v[66:67], v[66:67], v[70:71], v[76:77] op_sel_hi:[0,1,1]
	v_mul_f32_e32 v66, v69, v73
	v_pk_fma_f32 v[70:71], v[68:69], v[72:73], v[66:67] op_sel_hi:[1,1,0] neg_lo:[0,0,1] neg_hi:[0,0,1]
	v_mul_f32_e32 v66, v68, v73
	v_pk_fma_f32 v[72:73], v[68:69], v[72:73], v[66:67] op_sel:[1,0,0] op_sel_hi:[0,1,0]
	v_sub_f32_e32 v66, v74, v76
	v_mov_b32_e32 v68, v70
	v_mov_b32_e32 v69, v72
.LBB0_1435:
	s_or_b64 exec, exec, s[0:1]
	v_add_u32_e32 v71, 0x80, v136
	v_cvt_pk_bf16_f32 v72, v66, v67
	v_subrev_u32_e32 v66, s50, v71
	v_lshl_add_u32 v66, v66, 2, v201
	ds_read_b32 v66, v66
	s_mov_b32 s0, 0xff80
	v_cmp_gt_i32_e64 s[12:13], s0, v136
	v_lshlrev_b32_e32 v67, 5, v71
	v_cvt_pk_bf16_f32 v73, v68, v69
	v_and_b32_e32 v70, 0xf9e0, v67
	s_waitcnt lgkmcnt(0)
	v_pk_mul_f32 v[68:69], v[62:63], v[66:67] op_sel_hi:[1,0]
	v_pk_mul_f32 v[64:65], v[64:65], v[66:67] op_sel_hi:[1,0]
	s_and_b64 s[14:15], s[12:13], vcc
	global_store_dwordx2 v[102:103], v[72:73], off offset:288
	s_and_saveexec_b64 s[0:1], s[14:15]
	s_cbranch_execz .LBB0_1437
	v_add_lshl_u32 v62, v70, v137, 3
	v_mov_b32_e32 v72, v180
	v_mov_b32_e32 v73, v181
	v_mov_b32_e32 v74, v182
	v_mov_b32_e32 v75, v183
	v_pk_mul_f32 v[76:77], v[68:69], v[72:73] op_sel:[1,1] op_sel_hi:[1,0]
	v_pk_mul_f32 v[62:63], v[68:69], v[72:73]
	v_pk_fma_f32 v[68:69], v[68:69], v[72:73], v[76:77] op_sel_hi:[0,1,1]
	v_mul_f32_e32 v68, v65, v75
	v_pk_fma_f32 v[72:73], v[64:65], v[74:75], v[68:69] op_sel_hi:[1,1,0] neg_lo:[0,0,1] neg_hi:[0,0,1]
	v_mul_f32_e32 v68, v64, v75
	v_pk_fma_f32 v[74:75], v[64:65], v[74:75], v[68:69] op_sel:[1,0,0] op_sel_hi:[0,1,0]
	v_sub_f32_e32 v68, v62, v76
	v_mov_b32_e32 v64, v72
	v_mov_b32_e32 v65, v74
;   __device__ __forceinline__ void operator()(int m, int n, f32x4 v) const {
;     float r = srstd[m - m0];
;     v[0] *= r; v[1] *= r; v[2] *= r; v[3] *= r;
;     int h = n / 192, hc = n - h * 192;
;     if (hc >= 128 && m < TX) v = rope4(v, rope, m & 2047, (hc - 128) >> 1);
;     store4bf(Q + (size_t)m * 768 + n, v);
;   }
.LBB0_1437:
	s_or_b64 exec, exec, s[0:1]
	v_mov_b64_e32 v[62:63], s[94:95]
	s_movk_i32 s0, 0x600
	v_mov_b32_e32 v67, v66
	v_mad_i64_i32 v[62:63], s[0:1], v71, s0, v[62:63]
	v_lshl_add_u64 v[62:63], v[62:63], 0, v[0:1]
	v_cvt_pk_bf16_f32 v68, v68, v69
	v_cvt_pk_bf16_f32 v69, v64, v65
	v_pk_mul_f32 v[58:59], v[58:59], v[66:67]
	v_pk_mul_f32 v[60:61], v[60:61], v[66:67]
	s_and_b64 s[14:15], s[12:13], s[6:7]
	global_store_dwordx2 v[62:63], v[68:69], off
	s_and_saveexec_b64 s[0:1], s[14:15]
	s_cbranch_execz .LBB0_1439
	v_add_lshl_u32 v64, v70, v128, 3
	v_mov_b32_e32 v72, v184
	v_mov_b32_e32 v73, v185
	v_mov_b32_e32 v74, v186
	v_mov_b32_e32 v75, v187
	v_pk_mul_f32 v[68:69], v[58:59], v[72:73] op_sel:[1,1] op_sel_hi:[1,0]
	v_pk_mul_f32 v[64:65], v[58:59], v[72:73]
	v_pk_fma_f32 v[58:59], v[58:59], v[72:73], v[68:69] op_sel_hi:[0,1,1]
	v_mul_f32_e32 v58, v61, v75
	v_pk_fma_f32 v[72:73], v[60:61], v[74:75], v[58:59] op_sel_hi:[1,1,0] neg_lo:[0,0,1] neg_hi:[0,0,1]
	v_mul_f32_e32 v58, v60, v75
	v_pk_fma_f32 v[74:75], v[60:61], v[74:75], v[58:59] op_sel:[1,0,0] op_sel_hi:[0,1,0]
	v_sub_f32_e32 v58, v64, v68
	v_mov_b32_e32 v60, v72
	v_mov_b32_e32 v61, v74
.LBB0_1439:
	s_or_b64 exec, exec, s[0:1]
	v_add_u32_e32 v65, 0x90, v136
	v_cvt_pk_bf16_f32 v68, v58, v59
	v_subrev_u32_e32 v58, s50, v65
	v_lshl_add_u32 v58, v58, 2, v201
	ds_read_b32 v58, v58
	s_mov_b32 s0, 0xff70
	v_cmp_gt_i32_e64 s[14:15], s0, v136
	v_lshlrev_b32_e32 v59, 5, v65
	v_cvt_pk_bf16_f32 v69, v60, v61
	v_and_b32_e32 v64, 0xfbe0, v59
	s_waitcnt lgkmcnt(0)
	v_pk_mul_f32 v[60:61], v[54:55], v[58:59] op_sel_hi:[1,0]
	v_pk_mul_f32 v[56:57], v[56:57], v[58:59] op_sel_hi:[1,0]
	s_and_b64 s[16:17], s[14:15], vcc
	global_store_dwordx2 v[62:63], v[68:69], off offset:32
	s_and_saveexec_b64 s[0:1], s[16:17]
	s_cbranch_execz .LBB0_1441
	v_add_lshl_u32 v54, v64, v137, 3
	v_mov_b32_e32 v72, v188
	v_mov_b32_e32 v73, v189
	v_mov_b32_e32 v74, v190
	v_mov_b32_e32 v75, v191
	v_pk_mul_f32 v[68:69], v[60:61], v[72:73] op_sel:[1,1] op_sel_hi:[1,0]
	v_pk_mul_f32 v[54:55], v[60:61], v[72:73]
	v_pk_fma_f32 v[60:61], v[60:61], v[72:73], v[68:69] op_sel_hi:[0,1,1]
	v_mul_f32_e32 v60, v57, v75
	v_pk_fma_f32 v[72:73], v[56:57], v[74:75], v[60:61] op_sel_hi:[1,1,0] neg_lo:[0,0,1] neg_hi:[0,0,1]
	v_mul_f32_e32 v60, v56, v75
	v_pk_fma_f32 v[74:75], v[56:57], v[74:75], v[60:61] op_sel:[1,0,0] op_sel_hi:[0,1,0]
	v_sub_f32_e32 v60, v54, v68
	v_mov_b32_e32 v56, v72
	v_mov_b32_e32 v57, v74
.LBB0_1441:
	s_or_b64 exec, exec, s[0:1]
	v_mov_b64_e32 v[54:55], s[94:95]
	s_movk_i32 s0, 0x600
	v_mov_b32_e32 v59, v58
	v_mad_i64_i32 v[54:55], s[0:1], v65, s0, v[54:55]
	v_lshl_add_u64 v[54:55], v[54:55], 0, v[0:1]
	v_cvt_pk_bf16_f32 v60, v60, v61
	v_cvt_pk_bf16_f32 v61, v56, v57
	v_pk_mul_f32 v[50:51], v[50:51], v[58:59]
	v_pk_mul_f32 v[52:53], v[52:53], v[58:59]
	s_and_b64 s[16:17], s[14:15], s[6:7]
	global_store_dwordx2 v[54:55], v[60:61], off
	s_and_saveexec_b64 s[0:1], s[16:17]
	s_cbranch_execz .LBB0_1443
	v_add_lshl_u32 v56, v64, v128, 3
	v_mov_b32_e32 v72, v192
	v_mov_b32_e32 v73, v193
	v_mov_b32_e32 v74, v194
	v_mov_b32_e32 v75, v195
	v_pk_mul_f32 v[60:61], v[50:51], v[72:73] op_sel:[1,1] op_sel_hi:[1,0]
	v_pk_mul_f32 v[56:57], v[50:51], v[72:73]
	v_pk_fma_f32 v[50:51], v[50:51], v[72:73], v[60:61] op_sel_hi:[0,1,1]
	v_mul_f32_e32 v50, v53, v75
	v_pk_fma_f32 v[68:69], v[52:53], v[74:75], v[50:51] op_sel_hi:[1,1,0] neg_lo:[0,0,1] neg_hi:[0,0,1]
	v_mul_f32_e32 v50, v52, v75
	v_pk_fma_f32 v[72:73], v[52:53], v[74:75], v[50:51] op_sel:[1,0,0] op_sel_hi:[0,1,0]
	v_sub_f32_e32 v50, v56, v60
	v_mov_b32_e32 v52, v68
	v_mov_b32_e32 v53, v72
.LBB0_1443:
	s_or_b64 exec, exec, s[0:1]
	v_add_u32_e32 v57, 0xa0, v136
	v_cvt_pk_bf16_f32 v60, v50, v51
	v_subrev_u32_e32 v50, s50, v57
	v_lshl_add_u32 v50, v50, 2, v201
	ds_read_b32 v50, v50
	s_mov_b32 s0, 0xff60
	v_cmp_gt_i32_e64 s[16:17], s0, v136
	v_lshlrev_b32_e32 v51, 5, v57
	v_cvt_pk_bf16_f32 v61, v52, v53
	v_and_b32_e32 v56, 0xfde0, v51
	s_waitcnt lgkmcnt(0)
	v_pk_mul_f32 v[52:53], v[46:47], v[50:51] op_sel_hi:[1,0]
	v_pk_mul_f32 v[48:49], v[48:49], v[50:51] op_sel_hi:[1,0]
	s_and_b64 s[18:19], s[16:17], vcc
	global_store_dwordx2 v[54:55], v[60:61], off offset:32
	s_and_saveexec_b64 s[0:1], s[18:19]
	s_cbranch_execz .LBB0_1445
	v_add_lshl_u32 v46, v56, v137, 3
	v_mov_b32_e32 v72, v208
	v_mov_b32_e32 v73, v209
	v_mov_b32_e32 v74, v210
	v_mov_b32_e32 v75, v211
	v_pk_mul_f32 v[60:61], v[52:53], v[72:73] op_sel:[1,1] op_sel_hi:[1,0]
	v_pk_mul_f32 v[46:47], v[52:53], v[72:73]
	v_pk_fma_f32 v[52:53], v[52:53], v[72:73], v[60:61] op_sel_hi:[0,1,1]
	v_mul_f32_e32 v52, v49, v75
	v_pk_fma_f32 v[68:69], v[48:49], v[74:75], v[52:53] op_sel_hi:[1,1,0] neg_lo:[0,0,1] neg_hi:[0,0,1]
	v_mul_f32_e32 v52, v48, v75
	v_pk_fma_f32 v[72:73], v[48:49], v[74:75], v[52:53] op_sel:[1,0,0] op_sel_hi:[0,1,0]
	v_sub_f32_e32 v52, v46, v60
	v_mov_b32_e32 v48, v68
	v_mov_b32_e32 v49, v72
.LBB0_1445:
	s_or_b64 exec, exec, s[0:1]
	v_mov_b64_e32 v[46:47], s[94:95]
	s_movk_i32 s0, 0x600
	v_mov_b32_e32 v51, v50
	v_mad_i64_i32 v[46:47], s[0:1], v57, s0, v[46:47]
	v_lshl_add_u64 v[46:47], v[46:47], 0, v[0:1]
	v_cvt_pk_bf16_f32 v52, v52, v53
	v_cvt_pk_bf16_f32 v53, v48, v49
	v_pk_mul_f32 v[42:43], v[42:43], v[50:51]
	v_pk_mul_f32 v[44:45], v[44:45], v[50:51]
	s_and_b64 s[18:19], s[16:17], s[6:7]
	global_store_dwordx2 v[46:47], v[52:53], off
	s_and_saveexec_b64 s[0:1], s[18:19]
	s_cbranch_execz .LBB0_1447
	v_add_lshl_u32 v48, v56, v128, 3
	v_mov_b32_e32 v72, v212
	v_mov_b32_e32 v73, v213
	v_mov_b32_e32 v74, v214
	v_mov_b32_e32 v75, v215
	v_pk_mul_f32 v[52:53], v[42:43], v[72:73] op_sel:[1,1] op_sel_hi:[1,0]
	v_pk_mul_f32 v[48:49], v[42:43], v[72:73]
	v_pk_fma_f32 v[42:43], v[42:43], v[72:73], v[52:53] op_sel_hi:[0,1,1]
	v_mul_f32_e32 v42, v45, v75
	v_pk_fma_f32 v[60:61], v[44:45], v[74:75], v[42:43] op_sel_hi:[1,1,0] neg_lo:[0,0,1] neg_hi:[0,0,1]
	v_mul_f32_e32 v42, v44, v75
	v_pk_fma_f32 v[68:69], v[44:45], v[74:75], v[42:43] op_sel:[1,0,0] op_sel_hi:[0,1,0]
	v_sub_f32_e32 v42, v48, v52
	v_mov_b32_e32 v44, v60
	v_mov_b32_e32 v45, v68
;   __device__ __forceinline__ void operator()(int m, int n, f32x4 v) const {
;     float r = srstd[m - m0];
;     v[0] *= r; v[1] *= r; v[2] *= r; v[3] *= r;
;     int h = n / 192, hc = n - h * 192;
;     if (hc >= 128 && m < TX) v = rope4(v, rope, m & 2047, (hc - 128) >> 1);
;     store4bf(Q + (size_t)m * 768 + n, v);
;   }
.LBB0_1447:
	s_or_b64 exec, exec, s[0:1]
	v_add_u32_e32 v49, 0xb0, v136
	v_cvt_pk_bf16_f32 v52, v42, v43
	v_subrev_u32_e32 v42, s50, v49
	v_lshl_add_u32 v42, v42, 2, v201
	ds_read_b32 v42, v42
	s_mov_b32 s0, 0xff50
	v_cmp_gt_i32_e64 s[18:19], s0, v136
	v_lshlrev_b32_e32 v43, 5, v49
	v_cvt_pk_bf16_f32 v53, v44, v45
	v_and_b32_e32 v48, 0xffe0, v43
	s_waitcnt lgkmcnt(0)
	v_pk_mul_f32 v[44:45], v[38:39], v[42:43] op_sel_hi:[1,0]
	v_pk_mul_f32 v[40:41], v[40:41], v[42:43] op_sel_hi:[1,0]
	s_and_b64 s[46:47], s[18:19], vcc
	global_store_dwordx2 v[46:47], v[52:53], off offset:32
	s_and_saveexec_b64 s[0:1], s[46:47]
	s_cbranch_execz .LBB0_1449
	v_add_lshl_u32 v38, v48, v137, 3
	v_mov_b32_e32 v72, v216
	v_mov_b32_e32 v73, v217
	v_mov_b32_e32 v74, v218
	v_mov_b32_e32 v75, v219
	v_pk_mul_f32 v[52:53], v[44:45], v[72:73] op_sel:[1,1] op_sel_hi:[1,0]
	v_pk_mul_f32 v[38:39], v[44:45], v[72:73]
	v_pk_fma_f32 v[44:45], v[44:45], v[72:73], v[52:53] op_sel_hi:[0,1,1]
	v_mul_f32_e32 v44, v41, v75
	v_pk_fma_f32 v[60:61], v[40:41], v[74:75], v[44:45] op_sel_hi:[1,1,0] neg_lo:[0,0,1] neg_hi:[0,0,1]
	v_mul_f32_e32 v44, v40, v75
	v_pk_fma_f32 v[68:69], v[40:41], v[74:75], v[44:45] op_sel:[1,0,0] op_sel_hi:[0,1,0]
	v_sub_f32_e32 v44, v38, v52
	v_mov_b32_e32 v40, v60
	v_mov_b32_e32 v41, v68
.LBB0_1449:
	s_or_b64 exec, exec, s[0:1]
	v_mov_b64_e32 v[38:39], s[94:95]
	s_movk_i32 s0, 0x600
	v_mov_b32_e32 v43, v42
	v_mad_i64_i32 v[38:39], s[0:1], v49, s0, v[38:39]
	v_lshl_add_u64 v[38:39], v[38:39], 0, v[0:1]
	v_cvt_pk_bf16_f32 v44, v44, v45
	v_cvt_pk_bf16_f32 v45, v40, v41
	v_pk_mul_f32 v[34:35], v[34:35], v[42:43]
	v_pk_mul_f32 v[36:37], v[36:37], v[42:43]
	s_and_b64 s[6:7], s[18:19], s[6:7]
	global_store_dwordx2 v[38:39], v[44:45], off
	s_and_saveexec_b64 s[0:1], s[6:7]
	s_cbranch_execz .LBB0_1451
	v_add_lshl_u32 v0, v48, v128, 3
	v_mov_b32_e32 v72, v220
	v_mov_b32_e32 v73, v221
	v_mov_b32_e32 v74, v222
	v_mov_b32_e32 v75, v223
	v_mul_f32_e32 v0, v37, v75
	v_pk_mul_f32 v[44:45], v[34:35], v[72:73] op_sel:[1,1] op_sel_hi:[1,0]
	v_pk_fma_f32 v[52:53], v[36:37], v[74:75], v[0:1] op_sel_hi:[1,1,0] neg_lo:[0,0,1] neg_hi:[0,0,1]
	v_mul_f32_e32 v0, v36, v75
	v_pk_mul_f32 v[40:41], v[34:35], v[72:73]
	v_pk_fma_f32 v[34:35], v[34:35], v[72:73], v[44:45] op_sel_hi:[0,1,1]
	v_pk_fma_f32 v[60:61], v[36:37], v[74:75], v[0:1] op_sel:[1,0,0] op_sel_hi:[0,1,0]
	v_sub_f32_e32 v34, v40, v44
	v_mov_b32_e32 v36, v52
	v_mov_b32_e32 v37, v60
.LBB0_1451:
	s_or_b64 exec, exec, s[0:1]
	v_cvt_pk_bf16_f32 v34, v34, v35
	v_cvt_pk_bf16_f32 v35, v36, v37
	v_pk_mul_f32 v[30:31], v[30:31], v[66:67]
	v_pk_mul_f32 v[32:33], v[32:33], v[66:67]
	s_and_b64 s[6:7], s[12:13], s[8:9]
	global_store_dwordx2 v[38:39], v[34:35], off offset:32
	s_and_saveexec_b64 s[0:1], s[6:7]
	s_cbranch_execz .LBB0_1453
	v_add_lshl_u32 v0, v70, v98, 3
	v_mov_b32_e32 v34, v180
	v_mov_b32_e32 v35, v181
	v_mov_b32_e32 v36, v182
	v_mov_b32_e32 v37, v183
	v_pk_mul_f32 v[44:45], v[30:31], v[34:35] op_sel:[1,1] op_sel_hi:[1,0]
	v_mul_f32_e32 v0, v33, v37
	v_pk_mul_f32 v[40:41], v[30:31], v[34:35]
	v_pk_fma_f32 v[30:31], v[30:31], v[34:35], v[44:45] op_sel_hi:[0,1,1]
	v_pk_fma_f32 v[34:35], v[32:33], v[36:37], v[0:1] op_sel_hi:[1,1,0] neg_lo:[0,0,1] neg_hi:[0,0,1]
	v_mul_f32_e32 v0, v32, v37
	v_pk_fma_f32 v[36:37], v[32:33], v[36:37], v[0:1] op_sel:[1,0,0] op_sel_hi:[0,1,0]
	v_sub_f32_e32 v30, v40, v44
	v_mov_b32_e32 v32, v34
	v_mov_b32_e32 v33, v36
.LBB0_1453:
	s_or_b64 exec, exec, s[0:1]
	v_cvt_pk_bf16_f32 v30, v30, v31
	v_cvt_pk_bf16_f32 v31, v32, v33
	v_pk_mul_f32 v[26:27], v[26:27], v[66:67]
	v_pk_mul_f32 v[28:29], v[28:29], v[66:67]
	s_and_b64 s[6:7], s[12:13], s[10:11]
	global_store_dwordx2 v[62:63], v[30:31], off offset:256
	s_and_saveexec_b64 s[0:1], s[6:7]
	s_cbranch_execz .LBB0_1455
	v_add_lshl_u32 v0, v70, v94, 3
	v_mov_b32_e32 v30, v184
	v_mov_b32_e32 v31, v185
	v_mov_b32_e32 v32, v186
	v_mov_b32_e32 v33, v187
	v_pk_mul_f32 v[36:37], v[26:27], v[30:31] op_sel:[1,1] op_sel_hi:[1,0]
	v_mul_f32_e32 v0, v29, v33
	v_pk_mul_f32 v[34:35], v[26:27], v[30:31]
	v_pk_fma_f32 v[26:27], v[26:27], v[30:31], v[36:37] op_sel_hi:[0,1,1]
	v_pk_fma_f32 v[30:31], v[28:29], v[32:33], v[0:1] op_sel_hi:[1,1,0] neg_lo:[0,0,1] neg_hi:[0,0,1]
	v_mul_f32_e32 v0, v28, v33
	v_pk_fma_f32 v[32:33], v[28:29], v[32:33], v[0:1] op_sel:[1,0,0] op_sel_hi:[0,1,0]
	v_sub_f32_e32 v26, v34, v36
	v_mov_b32_e32 v28, v30
	v_mov_b32_e32 v29, v32
.LBB0_1455:
	s_or_b64 exec, exec, s[0:1]
	v_cvt_pk_bf16_f32 v26, v26, v27
	v_cvt_pk_bf16_f32 v27, v28, v29
	v_pk_mul_f32 v[22:23], v[22:23], v[58:59]
	v_pk_mul_f32 v[24:25], v[24:25], v[58:59]
	s_and_b64 s[6:7], s[14:15], s[8:9]
	global_store_dwordx2 v[62:63], v[26:27], off offset:288
	s_and_saveexec_b64 s[0:1], s[6:7]
	s_cbranch_execz .LBB0_1457
	v_add_lshl_u32 v0, v64, v98, 3
	v_mov_b32_e32 v26, v188
	v_mov_b32_e32 v27, v189
	v_mov_b32_e32 v28, v190
	v_mov_b32_e32 v29, v191
	v_pk_mul_f32 v[32:33], v[22:23], v[26:27] op_sel:[1,1] op_sel_hi:[1,0]
	v_mul_f32_e32 v0, v25, v29
	v_pk_mul_f32 v[30:31], v[22:23], v[26:27]
	v_pk_fma_f32 v[22:23], v[22:23], v[26:27], v[32:33] op_sel_hi:[0,1,1]
	v_pk_fma_f32 v[26:27], v[24:25], v[28:29], v[0:1] op_sel_hi:[1,1,0] neg_lo:[0,0,1] neg_hi:[0,0,1]
	v_mul_f32_e32 v0, v24, v29
	v_pk_fma_f32 v[28:29], v[24:25], v[28:29], v[0:1] op_sel:[1,0,0] op_sel_hi:[0,1,0]
	v_sub_f32_e32 v22, v30, v32
	v_mov_b32_e32 v24, v26
	v_mov_b32_e32 v25, v28
;   __device__ __forceinline__ void operator()(int m, int n, f32x4 v) const {
;     float r = srstd[m - m0];
;     v[0] *= r; v[1] *= r; v[2] *= r; v[3] *= r;
;     int h = n / 192, hc = n - h * 192;
;     if (hc >= 128 && m < TX) v = rope4(v, rope, m & 2047, (hc - 128) >> 1);
;     store4bf(Q + (size_t)m * 768 + n, v);
;   }
.LBB0_1457:
	s_or_b64 exec, exec, s[0:1]
	v_cvt_pk_bf16_f32 v22, v22, v23
	v_cvt_pk_bf16_f32 v23, v24, v25
	v_pk_mul_f32 v[18:19], v[18:19], v[58:59]
	v_pk_mul_f32 v[20:21], v[20:21], v[58:59]
	s_and_b64 s[6:7], s[14:15], s[10:11]
	global_store_dwordx2 v[54:55], v[22:23], off offset:256
	s_and_saveexec_b64 s[0:1], s[6:7]
	s_cbranch_execz .LBB0_1459
	v_add_lshl_u32 v0, v64, v94, 3
	v_mov_b32_e32 v22, v192
	v_mov_b32_e32 v23, v193
	v_mov_b32_e32 v24, v194
	v_mov_b32_e32 v25, v195
	v_pk_mul_f32 v[28:29], v[18:19], v[22:23] op_sel:[1,1] op_sel_hi:[1,0]
	v_mul_f32_e32 v0, v21, v25
	v_pk_mul_f32 v[26:27], v[18:19], v[22:23]
	v_pk_fma_f32 v[18:19], v[18:19], v[22:23], v[28:29] op_sel_hi:[0,1,1]
	v_pk_fma_f32 v[22:23], v[20:21], v[24:25], v[0:1] op_sel_hi:[1,1,0] neg_lo:[0,0,1] neg_hi:[0,0,1]
	v_mul_f32_e32 v0, v20, v25
	v_pk_fma_f32 v[24:25], v[20:21], v[24:25], v[0:1] op_sel:[1,0,0] op_sel_hi:[0,1,0]
	v_sub_f32_e32 v18, v26, v28
	v_mov_b32_e32 v20, v22
	v_mov_b32_e32 v21, v24
.LBB0_1459:
	s_or_b64 exec, exec, s[0:1]
	v_cvt_pk_bf16_f32 v18, v18, v19
	v_cvt_pk_bf16_f32 v19, v20, v21
	v_pk_mul_f32 v[14:15], v[14:15], v[50:51]
	v_pk_mul_f32 v[16:17], v[16:17], v[50:51]
	s_and_b64 s[6:7], s[16:17], s[8:9]
	global_store_dwordx2 v[54:55], v[18:19], off offset:288
	s_and_saveexec_b64 s[0:1], s[6:7]
	s_cbranch_execz .LBB0_1461
	v_add_lshl_u32 v0, v56, v98, 3
	v_mov_b32_e32 v18, v208
	v_mov_b32_e32 v19, v209
	v_mov_b32_e32 v20, v210
	v_mov_b32_e32 v21, v211
	v_pk_mul_f32 v[24:25], v[14:15], v[18:19] op_sel:[1,1] op_sel_hi:[1,0]
	v_mul_f32_e32 v0, v17, v21
	v_pk_mul_f32 v[22:23], v[14:15], v[18:19]
	v_pk_fma_f32 v[14:15], v[14:15], v[18:19], v[24:25] op_sel_hi:[0,1,1]
	v_pk_fma_f32 v[18:19], v[16:17], v[20:21], v[0:1] op_sel_hi:[1,1,0] neg_lo:[0,0,1] neg_hi:[0,0,1]
	v_mul_f32_e32 v0, v16, v21
	v_pk_fma_f32 v[20:21], v[16:17], v[20:21], v[0:1] op_sel:[1,0,0] op_sel_hi:[0,1,0]
	v_sub_f32_e32 v14, v22, v24
	v_mov_b32_e32 v16, v18
	v_mov_b32_e32 v17, v20
.LBB0_1461:
	s_or_b64 exec, exec, s[0:1]
	v_cvt_pk_bf16_f32 v14, v14, v15
	v_cvt_pk_bf16_f32 v15, v16, v17
	v_pk_mul_f32 v[10:11], v[10:11], v[50:51]
	v_pk_mul_f32 v[12:13], v[12:13], v[50:51]
	s_and_b64 s[6:7], s[16:17], s[10:11]
	global_store_dwordx2 v[46:47], v[14:15], off offset:256
	s_and_saveexec_b64 s[0:1], s[6:7]
	s_cbranch_execz .LBB0_1463
	v_add_lshl_u32 v0, v56, v94, 3
	v_mov_b32_e32 v14, v212
	v_mov_b32_e32 v15, v213
	v_mov_b32_e32 v16, v214
	v_mov_b32_e32 v17, v215
	v_pk_mul_f32 v[20:21], v[10:11], v[14:15] op_sel:[1,1] op_sel_hi:[1,0]
	v_mul_f32_e32 v0, v13, v17
	v_pk_mul_f32 v[18:19], v[10:11], v[14:15]
	v_pk_fma_f32 v[10:11], v[10:11], v[14:15], v[20:21] op_sel_hi:[0,1,1]
	v_pk_fma_f32 v[14:15], v[12:13], v[16:17], v[0:1] op_sel_hi:[1,1,0] neg_lo:[0,0,1] neg_hi:[0,0,1]
	v_mul_f32_e32 v0, v12, v17
	v_pk_fma_f32 v[16:17], v[12:13], v[16:17], v[0:1] op_sel:[1,0,0] op_sel_hi:[0,1,0]
	v_sub_f32_e32 v10, v18, v20
	v_mov_b32_e32 v12, v14
	v_mov_b32_e32 v13, v16
.LBB0_1463:
	s_or_b64 exec, exec, s[0:1]
	v_cvt_pk_bf16_f32 v10, v10, v11
	v_cvt_pk_bf16_f32 v11, v12, v13
	v_pk_mul_f32 v[6:7], v[6:7], v[42:43]
	v_pk_mul_f32 v[8:9], v[8:9], v[42:43]
	s_and_b64 s[6:7], s[18:19], s[8:9]
	global_store_dwordx2 v[46:47], v[10:11], off offset:288
	s_and_saveexec_b64 s[0:1], s[6:7]
	s_cbranch_execz .LBB0_1465
	v_add_lshl_u32 v0, v48, v98, 3
	v_mov_b32_e32 v10, v216
	v_mov_b32_e32 v11, v217
	v_mov_b32_e32 v12, v218
	v_mov_b32_e32 v13, v219
	v_pk_mul_f32 v[16:17], v[6:7], v[10:11] op_sel:[1,1] op_sel_hi:[1,0]
	v_mul_f32_e32 v0, v9, v13
	v_pk_mul_f32 v[14:15], v[6:7], v[10:11]
	v_pk_fma_f32 v[6:7], v[6:7], v[10:11], v[16:17] op_sel_hi:[0,1,1]
	v_pk_fma_f32 v[10:11], v[8:9], v[12:13], v[0:1] op_sel_hi:[1,1,0] neg_lo:[0,0,1] neg_hi:[0,0,1]
	v_mul_f32_e32 v0, v8, v13
	v_pk_fma_f32 v[12:13], v[8:9], v[12:13], v[0:1] op_sel:[1,0,0] op_sel_hi:[0,1,0]
	v_sub_f32_e32 v6, v14, v16
	v_mov_b32_e32 v8, v10
	v_mov_b32_e32 v9, v12
.LBB0_1465:
	s_or_b64 exec, exec, s[0:1]
	v_cvt_pk_bf16_f32 v6, v6, v7
	v_cvt_pk_bf16_f32 v7, v8, v9
	v_pk_mul_f32 v[2:3], v[2:3], v[42:43]
	v_pk_mul_f32 v[4:5], v[4:5], v[42:43]
	s_and_b64 s[6:7], s[18:19], s[10:11]
	global_store_dwordx2 v[38:39], v[6:7], off offset:256
	s_and_saveexec_b64 s[0:1], s[6:7]
	s_cbranch_execz .LBB0_1388
	v_add_lshl_u32 v0, v48, v94, 3
	v_mov_b32_e32 v6, v220
	v_mov_b32_e32 v7, v221
	v_mov_b32_e32 v8, v222
	v_mov_b32_e32 v9, v223
	v_pk_mul_f32 v[12:13], v[2:3], v[6:7] op_sel:[1,1] op_sel_hi:[1,0]
	v_mul_f32_e32 v0, v5, v9
	v_pk_mul_f32 v[10:11], v[2:3], v[6:7]
	v_pk_fma_f32 v[2:3], v[2:3], v[6:7], v[12:13] op_sel_hi:[0,1,1]
	v_pk_fma_f32 v[6:7], v[4:5], v[8:9], v[0:1] op_sel_hi:[1,1,0] neg_lo:[0,0,1] neg_hi:[0,0,1]
	v_mul_f32_e32 v0, v4, v9
	v_pk_fma_f32 v[8:9], v[4:5], v[8:9], v[0:1] op_sel:[1,0,0] op_sel_hi:[0,1,0]
	v_sub_f32_e32 v2, v10, v12
	v_mov_b32_e32 v4, v6
	v_mov_b32_e32 v5, v8
	s_branch .LBB0_1388

; __device__ __forceinline__ float lo_bf(unsigned u) { return __uint_as_float(u << 16); }
; __device__ __forceinline__ float hi_bf(unsigned u) { return __uint_as_float(u & 0xffff0000u); }
; __device__ __forceinline__ void cmlp_item(const Params& p, int j, int rt, int g, const u16* __restrict__ ZB, u16* sVT) {
;     ...
;   __syncthreads();
;   {
;     const int q = tid >> 1, half = tid & 1;
;     const u16* src = ZB + (size_t)(m0 + q) * 1024 + 512 + g * 128 + half * 64;
;     uint4 raw[8];
; #pragma unroll
;     for (int i = 0; i < 8; ++i) raw[i] = *(const uint4*)(src + i * 8);
;     float ss = 0.f;
; #pragma unroll
;     for (int i = 0; i < 8; ++i) {
;       unsigned w[4] = {raw[i].x, raw[i].y, raw[i].z, raw[i].w};
; #pragma unroll
;       for (int k = 0; k < 4; ++k) { float a = lo_bf(w[k]), b = hi_bf(w[k]); ss += a * a + b * b; }
;     }
;     ss += __shfl_xor(ss, 1);
;     const float rstd = rsqrtf(ss * (1.f / 128.f) + EPSV);
.LBB0_1553:
	v_mov_b32_e32 v38, v206
	s_and_b32 s9, s1, 0xffffff80
	v_bfe_u32 v0, v38, 1, 7
	v_or_b32_e32 v2, s9, v0
	v_ashrrev_i32_e32 v3, 31, v2
	s_and_b32 s10, s0, 3
	v_lshlrev_b64 v[2:3], 11, v[2:3]
	v_lshlrev_b32_e32 v0, 6, v38
	v_lshl_add_u64 v[2:3], s[92:93], 0, v[2:3]
	s_lshl_b32 s34, s10, 8
	v_and_b32_e32 v39, 64, v0
	v_lshl_add_u64 v[2:3], v[2:3], 0, s[34:35]
	v_lshlrev_b32_e32 v0, 1, v39
	v_lshl_add_u64 v[30:31], v[2:3], 0, v[0:1]
	s_waitcnt vmcnt(0)
	s_barrier
	global_load_dwordx4 v[2:5], v[30:31], off offset:1072
	global_load_dwordx4 v[6:9], v[30:31], off offset:1056
	global_load_dwordx4 v[10:13], v[30:31], off offset:1040
	global_load_dwordx4 v[14:17], v[30:31], off offset:1024
	global_load_dwordx4 v[18:21], v[30:31], off offset:1104
	global_load_dwordx4 v[22:25], v[30:31], off offset:1088
	global_load_dwordx4 v[26:29], v[30:31], off offset:1136
	s_nop 0
	global_load_dwordx4 v[30:33], v[30:31], off offset:1120
	s_lshl_b32 s6, s10, 9
	s_add_u32 s6, s14, s6
	s_addc_u32 s7, s15, 0
	v_lshlrev_b32_e32 v87, 2, v39
	s_or_b32 s10, s10, s16
	v_and_b32_e32 v67, 15, v38
	v_bfe_u32 v66, v38, 6, 2
	s_waitcnt vmcnt(7)
	v_and_b32_e32 v64, 0xffff0000, v2
	s_waitcnt vmcnt(6)
	v_and_b32_e32 v56, 0xffff0000, v6
	s_waitcnt vmcnt(5)
	v_and_b32_e32 v48, 0xffff0000, v10
	s_waitcnt vmcnt(4)
	v_and_b32_e32 v40, 0xffff0000, v14
	v_and_b32_e32 v42, 0xffff0000, v15
	v_lshlrev_b32_e32 v0, 16, v14
	v_mul_f32_e32 v14, v40, v40
	v_lshlrev_b32_e32 v41, 16, v15
	v_mul_f32_e32 v15, v42, v42
	v_fmac_f32_e32 v14, v0, v0
	v_fmac_f32_e32 v15, v41, v41
	v_and_b32_e32 v44, 0xffff0000, v16
	v_add_f32_e32 v14, v14, v15
	v_lshlrev_b32_e32 v43, 16, v16
	v_mul_f32_e32 v15, v44, v44
	v_fmac_f32_e32 v15, v43, v43
	v_and_b32_e32 v46, 0xffff0000, v17
	v_add_f32_e32 v14, v14, v15
	v_lshlrev_b32_e32 v45, 16, v17
	v_mul_f32_e32 v15, v46, v46
	v_fmac_f32_e32 v15, v45, v45
	v_lshlrev_b32_e32 v47, 16, v10
	v_mul_f32_e32 v10, v48, v48
	v_and_b32_e32 v50, 0xffff0000, v11
	v_add_f32_e32 v14, v14, v15
	v_fmac_f32_e32 v10, v47, v47
	v_lshlrev_b32_e32 v49, 16, v11
	v_mul_f32_e32 v11, v50, v50
	v_add_f32_e32 v10, v14, v10
	v_fmac_f32_e32 v11, v49, v49
	v_and_b32_e32 v52, 0xffff0000, v12
	v_add_f32_e32 v10, v10, v11
	v_lshlrev_b32_e32 v51, 16, v12
	v_mul_f32_e32 v11, v52, v52
	v_fmac_f32_e32 v11, v51, v51
	v_and_b32_e32 v54, 0xffff0000, v13
	v_add_f32_e32 v10, v10, v11
	v_lshlrev_b32_e32 v53, 16, v13
	v_mul_f32_e32 v11, v54, v54
	v_fmac_f32_e32 v11, v53, v53
	v_lshlrev_b32_e32 v55, 16, v6
	v_mul_f32_e32 v6, v56, v56
	v_and_b32_e32 v58, 0xffff0000, v7
	v_add_f32_e32 v10, v10, v11
	v_fmac_f32_e32 v6, v55, v55
	v_lshlrev_b32_e32 v57, 16, v7
	v_mul_f32_e32 v7, v58, v58
	v_add_f32_e32 v6, v10, v6
	v_fmac_f32_e32 v7, v57, v57
	v_and_b32_e32 v60, 0xffff0000, v8
	v_add_f32_e32 v6, v6, v7
	v_lshlrev_b32_e32 v59, 16, v8
	v_mul_f32_e32 v7, v60, v60
	v_fmac_f32_e32 v7, v59, v59
	v_and_b32_e32 v62, 0xffff0000, v9
	v_add_f32_e32 v6, v6, v7
	v_lshlrev_b32_e32 v61, 16, v9
	v_mul_f32_e32 v7, v62, v62
	v_fmac_f32_e32 v7, v61, v61
	v_lshlrev_b32_e32 v63, 16, v2
	v_mul_f32_e32 v2, v64, v64
	v_and_b32_e32 v68, 0xffff0000, v3
	v_add_f32_e32 v6, v6, v7
	v_fmac_f32_e32 v2, v63, v63
	v_lshlrev_b32_e32 v65, 16, v3
	v_mul_f32_e32 v3, v68, v68
	v_add_f32_e32 v2, v6, v2
	v_fmac_f32_e32 v3, v65, v65
	v_and_b32_e32 v70, 0xffff0000, v4
	v_add_f32_e32 v2, v2, v3
	v_lshlrev_b32_e32 v69, 16, v4
	v_mul_f32_e32 v3, v70, v70
	v_fmac_f32_e32 v3, v69, v69
	v_and_b32_e32 v73, 0xffff0000, v5
	v_add_f32_e32 v2, v2, v3
	v_lshlrev_b32_e32 v72, 16, v5
	v_mul_f32_e32 v3, v73, v73
	v_fmac_f32_e32 v3, v72, v72
	s_waitcnt vmcnt(2)
	v_and_b32_e32 v75, 0xffff0000, v22
	v_add_f32_e32 v2, v2, v3
	v_lshlrev_b32_e32 v74, 16, v22
	v_mul_f32_e32 v3, v75, v75
	v_fmac_f32_e32 v3, v74, v74
	v_and_b32_e32 v77, 0xffff0000, v23
	v_add_f32_e32 v2, v2, v3
	v_lshlrev_b32_e32 v76, 16, v23
	v_mul_f32_e32 v3, v77, v77
	v_fmac_f32_e32 v3, v76, v76
	v_and_b32_e32 v79, 0xffff0000, v24
	v_add_f32_e32 v2, v2, v3
	v_lshlrev_b32_e32 v78, 16, v24
	v_mul_f32_e32 v3, v79, v79
	v_fmac_f32_e32 v3, v78, v78
	v_and_b32_e32 v81, 0xffff0000, v25
	v_add_f32_e32 v2, v2, v3
	v_lshlrev_b32_e32 v80, 16, v25
	v_mul_f32_e32 v3, v81, v81
	v_fmac_f32_e32 v3, v80, v80
	v_and_b32_e32 v83, 0xffff0000, v18
	v_add_f32_e32 v2, v2, v3
	v_lshlrev_b32_e32 v82, 16, v18
	v_mul_f32_e32 v3, v83, v83
	v_fmac_f32_e32 v3, v82, v82
	v_and_b32_e32 v85, 0xffff0000, v19
	v_add_f32_e32 v2, v2, v3
	v_lshlrev_b32_e32 v84, 16, v19
	v_mul_f32_e32 v3, v85, v85
	v_fmac_f32_e32 v3, v84, v84
	v_and_b32_e32 v19, 0xffff0000, v21
	v_and_b32_e32 v18, 0xffff0000, v20
	v_add_f32_e32 v4, v2, v3
	v_lshlrev_b32_e32 v37, 16, v21
	v_lshlrev_b32_e32 v36, 16, v20
	v_pk_mul_f32 v[2:3], v[18:19], v[18:19]
	s_waitcnt vmcnt(0)
	v_and_b32_e32 v15, 0xffff0000, v31
	v_pk_fma_f32 v[2:3], v[36:37], v[36:37], v[2:3]
	v_and_b32_e32 v14, 0xffff0000, v30
	v_add_f32_e32 v2, v4, v2
	v_add_f32_e32 v4, v2, v3
	v_lshlrev_b32_e32 v17, 16, v31
	v_lshlrev_b32_e32 v16, 16, v30
	v_pk_mul_f32 v[2:3], v[14:15], v[14:15]
	v_and_b32_e32 v11, 0xffff0000, v33
	v_pk_fma_f32 v[2:3], v[16:17], v[16:17], v[2:3]
	v_and_b32_e32 v10, 0xffff0000, v32
	v_add_f32_e32 v2, v4, v2
	v_add_f32_e32 v4, v2, v3
	v_lshlrev_b32_e32 v13, 16, v33
	v_lshlrev_b32_e32 v12, 16, v32
	v_pk_mul_f32 v[2:3], v[10:11], v[10:11]
	v_and_b32_e32 v7, 0xffff0000, v27
	v_pk_fma_f32 v[2:3], v[12:13], v[12:13], v[2:3]
	v_and_b32_e32 v6, 0xffff0000, v26
	v_add_f32_e32 v2, v4, v2
	v_add_f32_e32 v4, v2, v3
	v_lshlrev_b32_e32 v9, 16, v27
	v_lshlrev_b32_e32 v8, 16, v26
	v_pk_mul_f32 v[2:3], v[6:7], v[6:7]
	v_lshlrev_b32_e32 v5, 16, v29
	v_pk_fma_f32 v[2:3], v[8:9], v[8:9], v[2:3]
	s_nop 0
	v_add_f32_e32 v2, v4, v2
	v_add_f32_e32 v22, v2, v3
	v_and_b32_e32 v3, 0xffff0000, v29
	v_and_b32_e32 v2, 0xffff0000, v28
	v_lshlrev_b32_e32 v4, 16, v28
	v_pk_mul_f32 v[20:21], v[2:3], v[2:3]
	s_nop 0
	v_pk_fma_f32 v[20:21], v[4:5], v[4:5], v[20:21]
	s_nop 0
	v_add_f32_e32 v20, v22, v20
	v_add_f32_e32 v20, v20, v21
	ds_bpermute_b32 v21, v71, v20
	s_waitcnt lgkmcnt(0)
; __device__ __forceinline__ float lo_bf(unsigned u) { return __uint_as_float(u << 16); }
; __device__ __forceinline__ float hi_bf(unsigned u) { return __uint_as_float(u & 0xffff0000u); }
; __device__ __forceinline__ void cmlp_item(const Params& p, int j, int rt, int g, const u16* __restrict__ ZB, u16* sVT) {
;     ...
;     const float rstd = rsqrtf(ss * (1.f / 128.f) + EPSV);
;     const float* vn = p.cmlp_v_norm + j * 512 + g * 128 + half * 64;
; #pragma unroll
;     for (int i = 0; i < 8; ++i) {
;       unsigned w[4] = {raw[i].x, raw[i].y, raw[i].z, raw[i].w};
; #pragma unroll
;       for (int k = 0; k < 4; ++k) {
;         int d = i * 8 + k * 2;
;         sVT[(half * 64 + d) * 136 + q] = f2bf(lo_bf(w[k]) * rstd * vn[d]);
;         sVT[(half * 64 + d + 1) * 136 + q] = f2bf(hi_bf(w[k]) * rstd * vn[d + 1]);
;       }
;     }
	v_add_f32_e32 v20, v20, v21
	v_fmamk_f32 v20, v20, 0x3c000000, v252
	v_cmp_gt_f32_e32 vcc, s90, v20
	v_mul_f32_e32 v21, 0x4b800000, v20
	s_nop 0
	v_cndmask_b32_e32 v20, v20, v21, vcc
	v_rsq_f32_e32 v20, v20
	s_nop 0
	v_mul_f32_e32 v21, 0x45800000, v20
	v_cndmask_b32_e32 v86, v20, v21, vcc
	global_load_dwordx4 v[112:115], v87, s[6:7]
	global_load_dwordx4 v[116:119], v87, s[6:7] offset:16
	global_load_dwordx4 v[120:123], v87, s[6:7] offset:32
	global_load_dwordx4 v[124:127], v87, s[6:7] offset:48
	global_load_dwordx4 v[128:131], v87, s[6:7] offset:64
	global_load_dwordx4 v[132:135], v87, s[6:7] offset:80
	global_load_dwordx4 v[136:139], v87, s[6:7] offset:96
	global_load_dwordx4 v[140:143], v87, s[6:7] offset:112
	global_load_dwordx4 v[144:147], v87, s[6:7] offset:128
	global_load_dwordx4 v[148:151], v87, s[6:7] offset:144
	global_load_dwordx4 v[152:155], v87, s[6:7] offset:160
	global_load_dwordx4 v[156:159], v87, s[6:7] offset:176
	global_load_dwordx4 v[160:163], v87, s[6:7] offset:192
	global_load_dwordx4 v[164:167], v87, s[6:7] offset:208
	global_load_dwordx4 v[168:171], v87, s[6:7] offset:224
	global_load_dwordx4 v[172:175], v87, s[6:7] offset:240
	v_mul_f32_e32 v0, v86, v0
	s_waitcnt vmcnt(0)
	v_mov_b32_e32 v20, v124
	v_mov_b32_e32 v21, v125
	v_mov_b32_e32 v22, v126
	v_mov_b32_e32 v23, v127
	v_mov_b32_e32 v24, v120
	v_mov_b32_e32 v25, v121
	v_mov_b32_e32 v26, v122
	v_mov_b32_e32 v27, v123
	v_mov_b32_e32 v28, v116
	v_mov_b32_e32 v29, v117
	v_mov_b32_e32 v30, v118
	v_mov_b32_e32 v31, v119
	v_mov_b32_e32 v32, v112
	v_mov_b32_e32 v33, v113
	v_mov_b32_e32 v34, v114
	v_mov_b32_e32 v35, v115
	v_mul_f32_e32 v0, v32, v0
	v_mul_u32_u24_e32 v32, 0x88, v39
	v_lshlrev_b32_e32 v32, 1, v32
	v_and_b32_e32 v39, 0xfe, v38
	v_cvt_pk_bf16_f32 v0, v0, s0
	v_add3_u32 v88, s58, v32, v39
	ds_write_b16 v88, v0
	v_mul_f32_e32 v0, v86, v40
	v_mul_f32_e32 v0, v33, v0
	v_cvt_pk_bf16_f32 v0, v0, s0
	v_add3_u32 v39, s58, v39, v32
	ds_write_b16 v39, v0 offset:272
	v_mul_f32_e32 v0, v86, v41
	v_mul_f32_e32 v0, v34, v0
	v_cvt_pk_bf16_f32 v0, v0, s0
	ds_write_b16 v88, v0 offset:544
	v_mul_f32_e32 v0, v86, v42
	v_mul_f32_e32 v0, v35, v0
	v_cvt_pk_bf16_f32 v0, v0, s0
	ds_write_b16 v39, v0 offset:816
	v_mul_f32_e32 v0, v86, v43
	v_mul_f32_e32 v0, v28, v0
	v_cvt_pk_bf16_f32 v0, v0, s0
	ds_write_b16 v88, v0 offset:1088
	v_mul_f32_e32 v0, v86, v44
	v_mul_f32_e32 v0, v0, v29
	v_cvt_pk_bf16_f32 v0, v0, s0
	ds_write_b16 v39, v0 offset:1360
	v_mul_f32_e32 v0, v86, v45
	v_mul_f32_e32 v0, v0, v30
	v_cvt_pk_bf16_f32 v0, v0, s0
	ds_write_b16 v88, v0 offset:1632
	v_mul_f32_e32 v0, v86, v46
	v_mul_f32_e32 v0, v0, v31
	v_cvt_pk_bf16_f32 v0, v0, s0
	ds_write_b16 v39, v0 offset:1904
	v_mul_f32_e32 v0, v86, v47
	v_mul_f32_e32 v0, v0, v24
	v_cvt_pk_bf16_f32 v0, v0, s0
	ds_write_b16 v88, v0 offset:2176
	v_mul_f32_e32 v0, v86, v48
	v_mul_f32_e32 v0, v0, v25
	v_cvt_pk_bf16_f32 v0, v0, s0
	ds_write_b16 v39, v0 offset:2448
	v_mul_f32_e32 v0, v86, v49
	v_mul_f32_e32 v0, v0, v26
	v_cvt_pk_bf16_f32 v0, v0, s0
	ds_write_b16 v88, v0 offset:2720
	v_mul_f32_e32 v0, v86, v50
	v_mul_f32_e32 v0, v0, v27
	v_cvt_pk_bf16_f32 v0, v0, s0
	ds_write_b16 v39, v0 offset:2992
	v_mul_f32_e32 v0, v86, v51
	v_mul_f32_e32 v0, v0, v20
	v_cvt_pk_bf16_f32 v0, v0, s0
	ds_write_b16 v88, v0 offset:3264
	v_mul_f32_e32 v0, v86, v52
	v_mul_f32_e32 v0, v0, v21
	v_cvt_pk_bf16_f32 v0, v0, s0
	ds_write_b16 v39, v0 offset:3536
	v_mul_f32_e32 v0, v86, v53
	v_mul_f32_e32 v0, v0, v22
	v_cvt_pk_bf16_f32 v0, v0, s0
	ds_write_b16 v88, v0 offset:3808
	v_mul_f32_e32 v0, v86, v54
	v_mul_f32_e32 v0, v0, v23
	v_cvt_pk_bf16_f32 v0, v0, s0
	ds_write_b16 v39, v0 offset:4080
	v_mul_f32_e32 v0, v86, v55
	s_waitcnt vmcnt(0)
	v_mov_b32_e32 v20, v140
	v_mov_b32_e32 v21, v141
	v_mov_b32_e32 v22, v142
	v_mov_b32_e32 v23, v143
	v_mov_b32_e32 v24, v136
	v_mov_b32_e32 v25, v137
	v_mov_b32_e32 v26, v138
	v_mov_b32_e32 v27, v139
	v_mov_b32_e32 v28, v132
	v_mov_b32_e32 v29, v133
	v_mov_b32_e32 v30, v134
	v_mov_b32_e32 v31, v135
	v_mov_b32_e32 v32, v128
	v_mov_b32_e32 v33, v129
	v_mov_b32_e32 v34, v130
	v_mov_b32_e32 v35, v131
	v_mul_f32_e32 v0, v0, v32
	v_cvt_pk_bf16_f32 v0, v0, s0
	ds_write_b16 v88, v0 offset:4352
	v_mul_f32_e32 v0, v86, v56
	v_mul_f32_e32 v0, v0, v33
	v_cvt_pk_bf16_f32 v0, v0, s0
	ds_write_b16 v39, v0 offset:4624
	v_mul_f32_e32 v0, v86, v57
	v_mul_f32_e32 v0, v0, v34
	v_cvt_pk_bf16_f32 v0, v0, s0
	ds_write_b16 v88, v0 offset:4896
	v_mul_f32_e32 v0, v86, v58
	v_mul_f32_e32 v0, v0, v35
	v_cvt_pk_bf16_f32 v0, v0, s0
	ds_write_b16 v39, v0 offset:5168
	v_mul_f32_e32 v0, v86, v59
	v_mul_f32_e32 v0, v0, v28
	v_cvt_pk_bf16_f32 v0, v0, s0
	ds_write_b16 v88, v0 offset:5440
	v_mul_f32_e32 v0, v86, v60
	v_mul_f32_e32 v0, v0, v29
	v_cvt_pk_bf16_f32 v0, v0, s0
	ds_write_b16 v39, v0 offset:5712
	v_mul_f32_e32 v0, v86, v61
	v_mul_f32_e32 v0, v0, v30
	v_cvt_pk_bf16_f32 v0, v0, s0
	ds_write_b16 v88, v0 offset:5984
	v_mul_f32_e32 v0, v86, v62
	v_mul_f32_e32 v0, v0, v31
	v_cvt_pk_bf16_f32 v0, v0, s0
	ds_write_b16 v39, v0 offset:6256
	v_mul_f32_e32 v0, v86, v63
	v_mul_f32_e32 v0, v0, v24
	v_cvt_pk_bf16_f32 v0, v0, s0
	ds_write_b16 v88, v0 offset:6528
	v_mul_f32_e32 v0, v86, v64
	v_mul_f32_e32 v0, v0, v25
	v_cvt_pk_bf16_f32 v0, v0, s0
	ds_write_b16 v39, v0 offset:6800
	v_mul_f32_e32 v0, v86, v65
	v_mul_f32_e32 v0, v0, v26
	v_cvt_pk_bf16_f32 v0, v0, s0
	ds_write_b16 v88, v0 offset:7072
	v_mul_f32_e32 v0, v86, v68
	v_mul_f32_e32 v0, v0, v27
	v_cvt_pk_bf16_f32 v0, v0, s0
	ds_write_b16 v39, v0 offset:7344
	v_mul_f32_e32 v0, v86, v69
	v_mul_f32_e32 v0, v0, v20
	v_cvt_pk_bf16_f32 v0, v0, s0
	ds_write_b16 v88, v0 offset:7616
	v_mul_f32_e32 v0, v86, v70
	v_mul_f32_e32 v0, v0, v21
	v_cvt_pk_bf16_f32 v0, v0, s0
	ds_write_b16 v39, v0 offset:7888
	v_mul_f32_e32 v0, v86, v72
	v_mul_f32_e32 v0, v0, v22
	v_cvt_pk_bf16_f32 v0, v0, s0
	ds_write_b16 v88, v0 offset:8160
	v_mul_f32_e32 v0, v86, v73
	v_mul_f32_e32 v0, v0, v23
	v_cvt_pk_bf16_f32 v0, v0, s0
	ds_write_b16 v39, v0 offset:8432
	v_mul_f32_e32 v0, v86, v74
	s_waitcnt vmcnt(0)
; __device__ __forceinline__ float lo_bf(unsigned u) { return __uint_as_float(u << 16); }
; __device__ __forceinline__ float hi_bf(unsigned u) { return __uint_as_float(u & 0xffff0000u); }
; __device__ __forceinline__ void cmlp_item(const Params& p, int j, int rt, int g, const u16* __restrict__ ZB, u16* sVT) {
;     ...
; #pragma unroll
;     for (int i = 0; i < 8; ++i) {
;       unsigned w[4] = {raw[i].x, raw[i].y, raw[i].z, raw[i].w};
; #pragma unroll
;       for (int k = 0; k < 4; ++k) {
;         int d = i * 8 + k * 2;
;         sVT[(half * 64 + d) * 136 + q] = f2bf(lo_bf(w[k]) * rstd * vn[d]);
;         sVT[(half * 64 + d + 1) * 136 + q] = f2bf(hi_bf(w[k]) * rstd * vn[d + 1]);
;       }
;     }
;   }
;   __syncthreads();
;   f32x4 acc[2][8];
; #pragma unroll
;   for (int a = 0; a < 2; ++a)
; #pragma unroll
;     for (int b = 0; b < 8; ++b) acc[a][b] = (f32x4){0.f, 0.f, 0.f, 0.f};
;   const float* wsb = p.cmlp_ws + (size_t)(j * 4 + g) * 128 * 128;
	v_mov_b32_e32 v20, v156
	v_mov_b32_e32 v21, v157
	v_mov_b32_e32 v22, v158
	v_mov_b32_e32 v23, v159
	v_mov_b32_e32 v24, v152
	v_mov_b32_e32 v25, v153
	v_mov_b32_e32 v26, v154
	v_mov_b32_e32 v27, v155
	v_mov_b32_e32 v28, v148
	v_mov_b32_e32 v29, v149
	v_mov_b32_e32 v30, v150
	v_mov_b32_e32 v31, v151
	v_mov_b32_e32 v32, v144
	v_mov_b32_e32 v33, v145
	v_mov_b32_e32 v34, v146
	v_mov_b32_e32 v35, v147
	v_mul_f32_e32 v0, v0, v32
	v_cvt_pk_bf16_f32 v0, v0, s0
	ds_write_b16 v88, v0 offset:8704
	v_mul_f32_e32 v0, v86, v75
	v_mul_f32_e32 v0, v0, v33
	v_cvt_pk_bf16_f32 v0, v0, s0
	ds_write_b16 v39, v0 offset:8976
	v_mul_f32_e32 v0, v86, v76
	v_mul_f32_e32 v0, v0, v34
	v_cvt_pk_bf16_f32 v0, v0, s0
	ds_write_b16 v88, v0 offset:9248
	v_mul_f32_e32 v0, v86, v77
	v_mul_f32_e32 v0, v0, v35
	v_cvt_pk_bf16_f32 v0, v0, s0
	ds_write_b16 v39, v0 offset:9520
	v_mul_f32_e32 v0, v86, v78
	v_mul_f32_e32 v0, v0, v28
	v_cvt_pk_bf16_f32 v0, v0, s0
	ds_write_b16 v88, v0 offset:9792
	v_mul_f32_e32 v0, v86, v79
	v_mul_f32_e32 v0, v0, v29
	v_cvt_pk_bf16_f32 v0, v0, s0
	ds_write_b16 v39, v0 offset:10064
	v_mul_f32_e32 v0, v86, v80
	v_mul_f32_e32 v0, v0, v30
	v_cvt_pk_bf16_f32 v0, v0, s0
	ds_write_b16 v88, v0 offset:10336
	v_mul_f32_e32 v0, v86, v81
	v_mul_f32_e32 v0, v0, v31
	v_cvt_pk_bf16_f32 v0, v0, s0
	ds_write_b16 v39, v0 offset:10608
	v_mul_f32_e32 v0, v86, v82
	v_mul_f32_e32 v0, v0, v24
	v_cvt_pk_bf16_f32 v0, v0, s0
	ds_write_b16 v88, v0 offset:10880
	v_mul_f32_e32 v0, v86, v83
	v_mul_f32_e32 v0, v0, v25
	v_cvt_pk_bf16_f32 v0, v0, s0
	ds_write_b16 v39, v0 offset:11152
	v_mul_f32_e32 v0, v86, v84
	v_mul_f32_e32 v0, v0, v26
	v_cvt_pk_bf16_f32 v0, v0, s0
	ds_write_b16 v88, v0 offset:11424
	v_mul_f32_e32 v0, v86, v85
	v_mul_f32_e32 v0, v0, v27
	v_cvt_pk_bf16_f32 v0, v0, s0
	ds_write_b16 v39, v0 offset:11696
	v_mul_f32_e32 v0, v86, v36
	v_mul_f32_e32 v0, v0, v20
	v_cvt_pk_bf16_f32 v0, v0, s0
	ds_write_b16 v88, v0 offset:11968
	v_mul_f32_e32 v0, v86, v18
	v_mul_f32_e32 v0, v0, v21
	v_cvt_pk_bf16_f32 v0, v0, s0
	ds_write_b16 v39, v0 offset:12240
	v_mul_f32_e32 v0, v86, v37
	v_mul_f32_e32 v0, v0, v22
	v_cvt_pk_bf16_f32 v0, v0, s0
	ds_write_b16 v88, v0 offset:12512
	v_mul_f32_e32 v0, v86, v19
	v_mul_f32_e32 v0, v0, v23
	v_cvt_pk_bf16_f32 v0, v0, s0
	ds_write_b16 v39, v0 offset:12784
	v_mul_f32_e32 v0, v86, v16
	s_lshl_b32 s6, s10, 16
	s_add_u32 s6, s46, s6
	s_addc_u32 s7, s47, 0
	s_waitcnt vmcnt(0)
	v_mov_b32_e32 v18, v172
	v_mov_b32_e32 v19, v173
	v_mov_b32_e32 v20, v174
	v_mov_b32_e32 v21, v175
	v_mov_b32_e32 v22, v168
	v_mov_b32_e32 v23, v169
	v_mov_b32_e32 v24, v170
	v_mov_b32_e32 v25, v171
	v_mov_b32_e32 v26, v164
	v_mov_b32_e32 v27, v165
	v_mov_b32_e32 v28, v166
	v_mov_b32_e32 v29, v167
	v_mov_b32_e32 v30, v160
	v_mov_b32_e32 v31, v161
	v_mov_b32_e32 v32, v162
	v_mov_b32_e32 v33, v163
	v_mul_f32_e32 v0, v0, v30
	v_cvt_pk_bf16_f32 v0, v0, s0
	ds_write_b16 v88, v0 offset:13056
	v_mul_f32_e32 v0, v86, v14
	v_mul_f32_e32 v0, v0, v31
	v_cvt_pk_bf16_f32 v0, v0, s0
	ds_write_b16 v39, v0 offset:13328
	v_mul_f32_e32 v0, v86, v17
	v_mul_f32_e32 v0, v0, v32
	v_cvt_pk_bf16_f32 v0, v0, s0
	ds_write_b16 v88, v0 offset:13600
	v_mul_f32_e32 v0, v86, v15
	v_mul_f32_e32 v0, v0, v33
	v_cvt_pk_bf16_f32 v0, v0, s0
	ds_write_b16 v39, v0 offset:13872
	v_mul_f32_e32 v0, v86, v12
	v_mul_f32_e32 v0, v0, v26
	v_cvt_pk_bf16_f32 v0, v0, s0
	ds_write_b16 v88, v0 offset:14144
	v_mul_f32_e32 v0, v86, v10
	v_mul_f32_e32 v0, v0, v27
	v_cvt_pk_bf16_f32 v0, v0, s0
	ds_write_b16 v39, v0 offset:14416
	v_mul_f32_e32 v0, v86, v13
	v_mul_f32_e32 v0, v0, v28
	v_cvt_pk_bf16_f32 v0, v0, s0
	ds_write_b16 v88, v0 offset:14688
	v_mul_f32_e32 v0, v86, v11
	v_mul_f32_e32 v0, v0, v29
	v_cvt_pk_bf16_f32 v0, v0, s0
	ds_write_b16 v39, v0 offset:14960
	v_mul_f32_e32 v0, v86, v8
	v_mul_f32_e32 v0, v0, v22
	v_cvt_pk_bf16_f32 v0, v0, s0
	ds_write_b16 v88, v0 offset:15232
	v_mul_f32_e32 v0, v86, v6
	v_mul_f32_e32 v0, v0, v23
	v_cvt_pk_bf16_f32 v0, v0, s0
	ds_write_b16 v39, v0 offset:15504
	v_mul_f32_e32 v0, v86, v9
	v_mul_f32_e32 v0, v0, v24
	v_cvt_pk_bf16_f32 v0, v0, s0
	ds_write_b16 v88, v0 offset:15776
	v_mul_f32_e32 v0, v86, v7
	v_mul_f32_e32 v0, v0, v25
	v_cvt_pk_bf16_f32 v0, v0, s0
	ds_write_b16 v39, v0 offset:16048
	v_mul_f32_e32 v0, v86, v4
	v_mul_f32_e32 v0, v0, v18
	v_cvt_pk_bf16_f32 v0, v0, s0
	ds_write_b16 v88, v0 offset:16320
	v_mul_f32_e32 v0, v86, v2
	v_mul_f32_e32 v0, v0, v19
	v_cvt_pk_bf16_f32 v0, v0, s0
	ds_write_b16 v39, v0 offset:16592
	v_mul_f32_e32 v0, v86, v5
	v_mul_f32_e32 v0, v0, v20
	v_cvt_pk_bf16_f32 v0, v0, s0
	v_bfe_u32 v4, v38, 4, 2
	ds_write_b16 v88, v0 offset:16864
	v_mul_f32_e32 v0, v86, v3
	v_lshlrev_b32_e32 v2, 5, v4
	v_mov_b32_e32 v3, v1
	v_lshl_add_u64 v[8:9], s[6:7], 0, v[2:3]
	v_lshlrev_b32_e32 v2, 9, v67
	v_mul_f32_e32 v0, v0, v21
	v_lshl_or_b32 v16, v66, 14, v2
	v_mov_b32_e32 v17, v1
	v_cvt_pk_bf16_f32 v0, v0, s0
	v_lshl_add_u64 v[10:11], v[8:9], 0, v[16:17]
	ds_write_b16 v39, v0 offset:17136
	s_waitcnt lgkmcnt(0)
	s_barrier
; __device__ __forceinline__ void cmlp_item(const Params& p, int j, int rt, int g, const u16* __restrict__ ZB, u16* sVT) {
;     ...
;   const float* wsb = p.cmlp_ws + (size_t)(j * 4 + g) * 128 * 128;
; #pragma unroll
;   for (int ks = 0; ks < 4; ++ks) {
;     bf16x8 wf[2];
; #pragma unroll
;     for (int pb = 0; pb < 2; ++pb) {
;       const float* wp = wsb + (size_t)(wave * 32 + pb * 16 + fr) * 128 + ks * 32 + fq * 8;
;       float4 a = *(const float4*)wp, b = *(const float4*)(wp + 4);
;       wf[pb] = mk8(pack2(a.x, a.y), pack2(a.z, a.w), pack2(b.x, b.y), pack2(b.z, b.w));
;     }
; #pragma unroll
;     for (int db = 0; db < 8; ++db) {
;       bf16x8 vf = *(const bf16x8*)(sVT + (db * 16 + fr) * 136 + ks * 32 + fq * 8);
; #pragma unroll
;       for (int pb = 0; pb < 2; ++pb) acc[pb][db] = mfma16(vf, wf[pb], acc[pb][db]);
;     }
;   }
	v_or_b32_e32 v176, 0x2000, v16
	v_mov_b32_e32 v177, v1
	v_lshl_add_u64 v[176:177], v[8:9], 0, v[176:177]
	global_load_dwordx4 v[112:115], v[10:11], off offset:16
	global_load_dwordx4 v[116:119], v[10:11], off
	global_load_dwordx4 v[120:123], v[176:177], off offset:16
	global_load_dwordx4 v[124:127], v[176:177], off
	global_load_dwordx4 v[128:131], v[10:11], off offset:144
	global_load_dwordx4 v[132:135], v[10:11], off offset:128
	global_load_dwordx4 v[136:139], v[176:177], off offset:144
	global_load_dwordx4 v[140:143], v[176:177], off offset:128
	global_load_dwordx4 v[144:147], v[10:11], off offset:272
	global_load_dwordx4 v[148:151], v[10:11], off offset:256
	global_load_dwordx4 v[152:155], v[176:177], off offset:272
	global_load_dwordx4 v[156:159], v[176:177], off offset:256
	global_load_dwordx4 v[160:163], v[10:11], off offset:400
	global_load_dwordx4 v[164:167], v[10:11], off offset:384
	global_load_dwordx4 v[168:171], v[176:177], off offset:400
	global_load_dwordx4 v[172:175], v[176:177], off offset:384
	v_lshlrev_b32_e32 v0, 3, v4
	v_lshlrev_b32_e32 v18, 4, v4
	s_add_u32 s6, s92, s34
	s_addc_u32 s7, s93, 0
	s_add_i32 s8, s8, s87
	s_add_i32 s1, s1, s11
	s_add_i32 s0, s0, s86
	s_cmpk_gt_i32 s8, 0x47f
	s_waitcnt vmcnt(0)
	v_mov_b32_e32 v4, v112
	v_mov_b32_e32 v5, v113
	v_mov_b32_e32 v6, v114
	v_mov_b32_e32 v7, v115
	v_mov_b32_e32 v12, v116
	v_mov_b32_e32 v13, v117
	v_mov_b32_e32 v14, v118
	v_mov_b32_e32 v15, v119
	v_cvt_pk_bf16_f32 v4, v4, v5
	v_cvt_pk_bf16_f32 v5, v6, v7
	v_or_b32_e32 v6, 0x2000, v16
	v_mov_b32_e32 v7, v1
	s_waitcnt vmcnt(0)
	v_cvt_pk_bf16_f32 v2, v12, v13
	v_lshl_add_u64 v[12:13], v[8:9], 0, v[6:7]
	v_cvt_pk_bf16_f32 v3, v14, v15
	s_waitcnt vmcnt(0)
	v_mov_b32_e32 v14, v120
	v_mov_b32_e32 v15, v121
	v_mov_b32_e32 v16, v122
	v_mov_b32_e32 v17, v123
	v_mov_b32_e32 v6, v124
	v_mov_b32_e32 v7, v125
	v_mov_b32_e32 v8, v126
	v_mov_b32_e32 v9, v127
	v_cvt_pk_bf16_f32 v6, v6, v7
	v_cvt_pk_bf16_f32 v7, v8, v9
	v_cvt_pk_bf16_f32 v8, v14, v15
	v_mul_u32_u24_e32 v14, 0x88, v67
	v_lshlrev_b32_e32 v14, 1, v14
	v_add3_u32 v34, s58, v18, v14
	v_cvt_pk_bf16_f32 v9, v16, v17
	ds_read_b128 v[14:17], v34
	ds_read_b128 v[22:25], v34 offset:4352
	ds_read_b128 v[30:33], v34 offset:8704
	ds_read_b128 v[40:43], v34 offset:13056
	ds_read_b128 v[48:51], v34 offset:17408
	ds_read_b128 v[56:59], v34 offset:21760
	ds_read_b128 v[72:75], v34 offset:26112
	ds_read_b128 v[80:83], v34 offset:30464
	s_waitcnt lgkmcnt(7)
	v_mfma_f32_16x16x32_bf16 v[18:21], v[14:17], v[2:5], 0
	v_mfma_f32_16x16x32_bf16 v[14:17], v[14:17], v[6:9], 0
	s_waitcnt lgkmcnt(6)
	v_mfma_f32_16x16x32_bf16 v[26:29], v[22:25], v[2:5], 0
	v_mfma_f32_16x16x32_bf16 v[22:25], v[22:25], v[6:9], 0
	s_waitcnt lgkmcnt(5)
	v_mfma_f32_16x16x32_bf16 v[36:39], v[30:33], v[2:5], 0
	v_mfma_f32_16x16x32_bf16 v[30:33], v[30:33], v[6:9], 0
	s_waitcnt lgkmcnt(4)
	v_mfma_f32_16x16x32_bf16 v[44:47], v[40:43], v[2:5], 0
	v_mfma_f32_16x16x32_bf16 v[40:43], v[40:43], v[6:9], 0
	s_waitcnt lgkmcnt(3)
	v_mfma_f32_16x16x32_bf16 v[52:55], v[48:51], v[2:5], 0
	v_mfma_f32_16x16x32_bf16 v[48:51], v[48:51], v[6:9], 0
	s_waitcnt lgkmcnt(2)
	v_mfma_f32_16x16x32_bf16 v[60:63], v[56:59], v[2:5], 0
	v_mfma_f32_16x16x32_bf16 v[56:59], v[56:59], v[6:9], 0
	s_waitcnt lgkmcnt(1)
	v_mfma_f32_16x16x32_bf16 v[76:79], v[72:75], v[2:5], 0
	v_mfma_f32_16x16x32_bf16 v[72:75], v[72:75], v[6:9], 0
	s_waitcnt lgkmcnt(0)
	v_mfma_f32_16x16x32_bf16 v[2:5], v[80:83], v[2:5], 0
	v_mfma_f32_16x16x32_bf16 v[6:9], v[80:83], v[6:9], 0
	s_waitcnt vmcnt(0)
	v_mov_b32_e32 v80, v128
	v_mov_b32_e32 v81, v129
	v_mov_b32_e32 v82, v130
	v_mov_b32_e32 v83, v131
	v_mov_b32_e32 v84, v132
	v_mov_b32_e32 v85, v133
	v_mov_b32_e32 v86, v134
	v_mov_b32_e32 v87, v135
	v_cvt_pk_bf16_f32 v84, v84, v85
	v_cvt_pk_bf16_f32 v85, v86, v87
	v_cvt_pk_bf16_f32 v86, v80, v81
	v_cvt_pk_bf16_f32 v87, v82, v83
	s_waitcnt vmcnt(0)
	v_mov_b32_e32 v80, v136
	v_mov_b32_e32 v81, v137
	v_mov_b32_e32 v82, v138
	v_mov_b32_e32 v83, v139
	v_mov_b32_e32 v88, v140
	v_mov_b32_e32 v89, v141
	v_mov_b32_e32 v90, v142
	v_mov_b32_e32 v91, v143
	v_cvt_pk_bf16_f32 v88, v88, v89
	v_cvt_pk_bf16_f32 v89, v90, v91
	v_cvt_pk_bf16_f32 v90, v80, v81
	v_cvt_pk_bf16_f32 v91, v82, v83
	ds_read_b128 v[80:83], v34 offset:64
	s_waitcnt lgkmcnt(0)
	v_mfma_f32_16x16x32_bf16 v[18:21], v[80:83], v[84:87], v[18:21]
	v_mfma_f32_16x16x32_bf16 v[14:17], v[80:83], v[88:91], v[14:17]
	ds_read_b128 v[80:83], v34 offset:4416
	s_waitcnt lgkmcnt(0)
	v_mfma_f32_16x16x32_bf16 v[26:29], v[80:83], v[84:87], v[26:29]
	v_mfma_f32_16x16x32_bf16 v[22:25], v[80:83], v[88:91], v[22:25]
	ds_read_b128 v[80:83], v34 offset:8768
	s_waitcnt lgkmcnt(0)
	v_mfma_f32_16x16x32_bf16 v[36:39], v[80:83], v[84:87], v[36:39]
	v_mfma_f32_16x16x32_bf16 v[30:33], v[80:83], v[88:91], v[30:33]
	ds_read_b128 v[80:83], v34 offset:13120
	s_waitcnt lgkmcnt(0)
	v_mfma_f32_16x16x32_bf16 v[44:47], v[80:83], v[84:87], v[44:47]
	v_mfma_f32_16x16x32_bf16 v[40:43], v[80:83], v[88:91], v[40:43]
	ds_read_b128 v[80:83], v34 offset:17472
	s_waitcnt lgkmcnt(0)
	v_mfma_f32_16x16x32_bf16 v[52:55], v[80:83], v[84:87], v[52:55]
	v_mfma_f32_16x16x32_bf16 v[48:51], v[80:83], v[88:91], v[48:51]
	ds_read_b128 v[80:83], v34 offset:21824
	s_waitcnt lgkmcnt(0)
	v_mfma_f32_16x16x32_bf16 v[60:63], v[80:83], v[84:87], v[60:63]
	v_mfma_f32_16x16x32_bf16 v[56:59], v[80:83], v[88:91], v[56:59]
	ds_read_b128 v[80:83], v34 offset:26176
	s_waitcnt lgkmcnt(0)
	v_mfma_f32_16x16x32_bf16 v[76:79], v[80:83], v[84:87], v[76:79]
	v_mfma_f32_16x16x32_bf16 v[72:75], v[80:83], v[88:91], v[72:75]
	ds_read_b128 v[80:83], v34 offset:30528
	s_waitcnt lgkmcnt(0)
; __device__ __forceinline__ void cmlp_item(const Params& p, int j, int rt, int g, const u16* __restrict__ ZB, u16* sVT) {
;     ...
;   for (int ks = 0; ks < 4; ++ks) {
;     bf16x8 wf[2];
; #pragma unroll
;     for (int pb = 0; pb < 2; ++pb) {
;       const float* wp = wsb + (size_t)(wave * 32 + pb * 16 + fr) * 128 + ks * 32 + fq * 8;
;       float4 a = *(const float4*)wp, b = *(const float4*)(wp + 4);
;       wf[pb] = mk8(pack2(a.x, a.y), pack2(a.z, a.w), pack2(b.x, b.y), pack2(b.z, b.w));
;     }
; #pragma unroll
;     for (int db = 0; db < 8; ++db) {
;       bf16x8 vf = *(const bf16x8*)(sVT + (db * 16 + fr) * 136 + ks * 32 + fq * 8);
; #pragma unroll
;       for (int pb = 0; pb < 2; ++pb) acc[pb][db] = mfma16(vf, wf[pb], acc[pb][db]);
;     }
;   }
; #pragma unroll
;   for (int pb = 0; pb < 2; ++pb) {
;     const int pp = wave * 32 + pb * 16 + fr;
;     const float bias = p.cmlp_bs[(j * 4 + g) * 128 + pp];
; #pragma unroll
;     for (int db = 0; db < 8; ++db) {
;       const int d = db * 16 + fq * 4;
;       uint2 uu = *(const uint2*)(ZB + (size_t)(m0 + pp) * 1024 + g * 128 + d);
	v_mfma_f32_16x16x32_bf16 v[2:5], v[80:83], v[84:87], v[2:5]
	v_mfma_f32_16x16x32_bf16 v[6:9], v[80:83], v[88:91], v[6:9]
	s_waitcnt vmcnt(0)
	v_mov_b32_e32 v80, v144
	v_mov_b32_e32 v81, v145
	v_mov_b32_e32 v82, v146
	v_mov_b32_e32 v83, v147
	v_mov_b32_e32 v84, v148
	v_mov_b32_e32 v85, v149
	v_mov_b32_e32 v86, v150
	v_mov_b32_e32 v87, v151
	v_cvt_pk_bf16_f32 v84, v84, v85
	v_cvt_pk_bf16_f32 v85, v86, v87
	v_cvt_pk_bf16_f32 v86, v80, v81
	v_cvt_pk_bf16_f32 v87, v82, v83
	s_waitcnt vmcnt(0)
	v_mov_b32_e32 v80, v152
	v_mov_b32_e32 v81, v153
	v_mov_b32_e32 v82, v154
	v_mov_b32_e32 v83, v155
	v_mov_b32_e32 v88, v156
	v_mov_b32_e32 v89, v157
	v_mov_b32_e32 v90, v158
	v_mov_b32_e32 v91, v159
	v_cvt_pk_bf16_f32 v88, v88, v89
	v_cvt_pk_bf16_f32 v89, v90, v91
	v_cvt_pk_bf16_f32 v90, v80, v81
	v_cvt_pk_bf16_f32 v91, v82, v83
	ds_read_b128 v[80:83], v34 offset:128
	s_waitcnt lgkmcnt(0)
	v_mfma_f32_16x16x32_bf16 v[18:21], v[80:83], v[84:87], v[18:21]
	v_mfma_f32_16x16x32_bf16 v[14:17], v[80:83], v[88:91], v[14:17]
	ds_read_b128 v[80:83], v34 offset:4480
	s_waitcnt lgkmcnt(0)
	v_mfma_f32_16x16x32_bf16 v[26:29], v[80:83], v[84:87], v[26:29]
	v_mfma_f32_16x16x32_bf16 v[22:25], v[80:83], v[88:91], v[22:25]
	ds_read_b128 v[80:83], v34 offset:8832
	s_waitcnt lgkmcnt(0)
	v_mfma_f32_16x16x32_bf16 v[36:39], v[80:83], v[84:87], v[36:39]
	v_mfma_f32_16x16x32_bf16 v[80:83], v[80:83], v[88:91], v[30:33]
	s_nop 2
	ds_read_b128 v[30:33], v34 offset:13184
	s_waitcnt lgkmcnt(0)
	v_mfma_f32_16x16x32_bf16 v[44:47], v[30:33], v[84:87], v[44:47]
	v_mfma_f32_16x16x32_bf16 v[40:43], v[30:33], v[88:91], v[40:43]
	ds_read_b128 v[30:33], v34 offset:17536
	s_waitcnt lgkmcnt(0)
	v_mfma_f32_16x16x32_bf16 v[92:95], v[30:33], v[84:87], v[52:55]
	v_mfma_f32_16x16x32_bf16 v[96:99], v[30:33], v[88:91], v[48:51]
	ds_read_b128 v[30:33], v34 offset:21888
	s_waitcnt lgkmcnt(0)
	v_mfma_f32_16x16x32_bf16 v[100:103], v[30:33], v[84:87], v[60:63]
	v_mfma_f32_16x16x32_bf16 v[104:107], v[30:33], v[88:91], v[56:59]
	ds_read_b128 v[30:33], v34 offset:26240
	s_waitcnt lgkmcnt(0)
	v_mfma_f32_16x16x32_bf16 v[76:79], v[30:33], v[84:87], v[76:79]
	v_mfma_f32_16x16x32_bf16 v[72:75], v[30:33], v[88:91], v[72:75]
	ds_read_b128 v[30:33], v34 offset:30592
	s_waitcnt lgkmcnt(0)
	v_mfma_f32_16x16x32_bf16 v[2:5], v[30:33], v[84:87], v[2:5]
	v_mfma_f32_16x16x32_bf16 v[84:87], v[30:33], v[88:91], v[6:9]
	s_nop 2
	s_waitcnt vmcnt(0)
	v_mov_b32_e32 v6, v160
	v_mov_b32_e32 v7, v161
	v_mov_b32_e32 v8, v162
	v_mov_b32_e32 v9, v163
	v_mov_b32_e32 v30, v164
	v_mov_b32_e32 v31, v165
	v_mov_b32_e32 v32, v166
	v_mov_b32_e32 v33, v167
	v_cvt_pk_bf16_f32 v90, v6, v7
	v_cvt_pk_bf16_f32 v91, v8, v9
	s_nop 0
	s_waitcnt vmcnt(0)
	v_mov_b32_e32 v6, v168
	v_mov_b32_e32 v7, v169
	v_mov_b32_e32 v8, v170
	v_mov_b32_e32 v9, v171
	v_mov_b32_e32 v10, v172
	v_mov_b32_e32 v11, v173
	v_mov_b32_e32 v12, v174
	v_mov_b32_e32 v13, v175
	v_cvt_pk_bf16_f32 v88, v30, v31
	v_cvt_pk_bf16_f32 v89, v32, v33
	s_waitcnt vmcnt(0)
	v_cvt_pk_bf16_f32 v110, v6, v7
	v_cvt_pk_bf16_f32 v111, v8, v9
	ds_read_b128 v[6:9], v34 offset:192
	s_waitcnt vmcnt(0)
	v_cvt_pk_bf16_f32 v108, v10, v11
	v_cvt_pk_bf16_f32 v109, v12, v13
	s_waitcnt lgkmcnt(0)
	v_mfma_f32_16x16x32_bf16 v[62:65], v[6:9], v[88:91], v[18:21]
	v_mfma_f32_16x16x32_bf16 v[30:33], v[6:9], v[108:111], v[14:17]
	ds_read_b128 v[6:9], v34 offset:4544
	s_waitcnt lgkmcnt(0)
	v_mfma_f32_16x16x32_bf16 v[58:61], v[6:9], v[88:91], v[26:29]
	v_mfma_f32_16x16x32_bf16 v[26:29], v[6:9], v[108:111], v[22:25]
	ds_read_b128 v[6:9], v34 offset:8896
	s_waitcnt lgkmcnt(0)
	v_mfma_f32_16x16x32_bf16 v[54:57], v[6:9], v[88:91], v[36:39]
	v_mfma_f32_16x16x32_bf16 v[22:25], v[6:9], v[108:111], v[80:83]
	ds_read_b128 v[6:9], v34 offset:13248
	s_waitcnt lgkmcnt(0)
	v_mfma_f32_16x16x32_bf16 v[50:53], v[6:9], v[88:91], v[44:47]
	v_mfma_f32_16x16x32_bf16 v[18:21], v[6:9], v[108:111], v[40:43]
	ds_read_b128 v[6:9], v34 offset:17600
	s_waitcnt lgkmcnt(0)
	v_mfma_f32_16x16x32_bf16 v[46:49], v[6:9], v[88:91], v[92:95]
	v_mfma_f32_16x16x32_bf16 v[14:17], v[6:9], v[108:111], v[96:99]
	ds_read_b128 v[6:9], v34 offset:21952
	s_waitcnt lgkmcnt(0)
	v_mfma_f32_16x16x32_bf16 v[42:45], v[6:9], v[88:91], v[100:103]
	v_mfma_f32_16x16x32_bf16 v[10:13], v[6:9], v[108:111], v[104:107]
	ds_read_b128 v[6:9], v34 offset:26304
	s_waitcnt lgkmcnt(0)
	v_mfma_f32_16x16x32_bf16 v[38:41], v[6:9], v[88:91], v[76:79]
	v_mfma_f32_16x16x32_bf16 v[6:9], v[6:9], v[108:111], v[72:75]
	s_nop 2
	ds_read_b128 v[72:75], v34 offset:30656
	s_waitcnt lgkmcnt(0)
	v_mfma_f32_16x16x32_bf16 v[34:37], v[72:75], v[88:91], v[2:5]
	v_mfma_f32_16x16x32_bf16 v[2:5], v[72:75], v[108:111], v[84:87]
	v_lshl_or_b32 v72, v66, 5, v67
	v_lshl_or_b32 v66, s10, 7, v72
	v_mov_b32_e32 v67, v1
	v_lshl_add_u64 v[68:69], v[66:67], 2, s[48:49]
	v_or_b32_e32 v66, s9, v72
	v_ashrrev_i32_e32 v67, 31, v66
	v_lshlrev_b64 v[76:77], 11, v[66:67]
	v_lshl_add_u64 v[72:73], s[6:7], 0, v[76:77]
	v_lshl_add_u64 v[72:73], v[72:73], 0, v[0:1]
	global_load_dword v70, v[68:69], off
	global_load_dwordx2 v[78:79], v[72:73], off
	global_load_dword v112, v[68:69], off offset:64
	global_load_dwordx2 v[114:115], v[72:73], off offset:32
	global_load_dwordx2 v[116:117], v[72:73], off offset:64
	global_load_dwordx2 v[118:119], v[72:73], off offset:96
	global_load_dwordx2 v[120:121], v[72:73], off offset:128
	global_load_dwordx2 v[122:123], v[72:73], off offset:160
	global_load_dwordx2 v[124:125], v[72:73], off offset:192
	global_load_dwordx2 v[126:127], v[72:73], off offset:224
	v_or_b32_e32 v144, 16, v66
	v_ashrrev_i32_e32 v145, 31, v144
	v_lshlrev_b64 v[144:145], 11, v[144:145]
	v_lshl_add_u64 v[144:145], s[6:7], 0, v[144:145]
	v_lshl_add_u64 v[144:145], v[144:145], 0, v[0:1]
	global_load_dwordx2 v[128:129], v[144:145], off
	global_load_dwordx2 v[130:131], v[144:145], off offset:32
	global_load_dwordx2 v[132:133], v[144:145], off offset:64
	global_load_dwordx2 v[134:135], v[144:145], off offset:96
	global_load_dwordx2 v[136:137], v[144:145], off offset:128
	global_load_dwordx2 v[138:139], v[144:145], off offset:160
	global_load_dwordx2 v[140:141], v[144:145], off offset:192
	global_load_dwordx2 v[142:143], v[144:145], off offset:224
	s_waitcnt vmcnt(0)
; __device__ __forceinline__ float lo_bf(unsigned u) { return __uint_as_float(u << 16); }
; __device__ __forceinline__ float hi_bf(unsigned u) { return __uint_as_float(u & 0xffff0000u); }
; __device__ __forceinline__ void cmlp_item(const Params& p, int j, int rt, int g, const u16* __restrict__ ZB, u16* sVT) {
;     ...
; #pragma unroll
;   for (int pb = 0; pb < 2; ++pb) {
;     const int pp = wave * 32 + pb * 16 + fr;
;     const float bias = p.cmlp_bs[(j * 4 + g) * 128 + pp];
; #pragma unroll
;     for (int db = 0; db < 8; ++db) {
;       const int d = db * 16 + fq * 4;
;       uint2 uu = *(const uint2*)(ZB + (size_t)(m0 + pp) * 1024 + g * 128 + d);
;       f32x4 r;
;       r[0] = lo_bf(uu.x) * (acc[pb][db][0] + bias);
;       r[1] = hi_bf(uu.x) * (acc[pb][db][1] + bias);
;       r[2] = lo_bf(uu.y) * (acc[pb][db][2] + bias);
;       r[3] = hi_bf(uu.y) * (acc[pb][db][3] + bias);
;       store4bf(p.XN + (size_t)(m0 + pp) * 1024 + 512 + g * 128 + d, r);
;     }
;   }
	v_pk_add_f32 v[62:63], v[62:63], v[70:71] op_sel_hi:[1,0]
	v_lshlrev_b32_e32 v74, 16, v78
	v_and_b32_e32 v75, 0xffff0000, v78
	v_pk_mul_f32 v[74:75], v[62:63], v[74:75]
	v_lshlrev_b32_e32 v62, 16, v79
	v_and_b32_e32 v63, 0xffff0000, v79
	v_pk_add_f32 v[64:65], v[64:65], v[70:71] op_sel_hi:[1,0]
	v_cvt_pk_bf16_f32 v74, v74, v75
	v_pk_mul_f32 v[64:65], v[64:65], v[62:63]
	v_lshl_add_u64 v[62:63], s[42:43], 0, v[76:77]
	v_lshl_add_u64 v[62:63], v[62:63], 0, s[34:35]
	v_lshl_add_u64 v[62:63], v[62:63], 0, v[0:1]
	v_cvt_pk_bf16_f32 v75, v64, v65
	global_store_dwordx2 v[62:63], v[74:75], off offset:1024
	v_mov_b32_e32 v64, v114
	v_mov_b32_e32 v65, v115
	v_pk_add_f32 v[58:59], v[58:59], v[70:71] op_sel_hi:[1,0]
	v_pk_add_f32 v[60:61], v[60:61], v[70:71] op_sel_hi:[1,0]
	v_pk_add_f32 v[54:55], v[54:55], v[70:71] op_sel_hi:[1,0]
	v_pk_add_f32 v[56:57], v[56:57], v[70:71] op_sel_hi:[1,0]
	v_pk_add_f32 v[50:51], v[50:51], v[70:71] op_sel_hi:[1,0]
	v_pk_add_f32 v[52:53], v[52:53], v[70:71] op_sel_hi:[1,0]
	v_pk_add_f32 v[46:47], v[46:47], v[70:71] op_sel_hi:[1,0]
	v_pk_add_f32 v[48:49], v[48:49], v[70:71] op_sel_hi:[1,0]
	v_pk_add_f32 v[42:43], v[42:43], v[70:71] op_sel_hi:[1,0]
	v_pk_add_f32 v[44:45], v[44:45], v[70:71] op_sel_hi:[1,0]
	v_pk_add_f32 v[38:39], v[38:39], v[70:71] op_sel_hi:[1,0]
	v_pk_add_f32 v[40:41], v[40:41], v[70:71] op_sel_hi:[1,0]
	v_pk_add_f32 v[34:35], v[34:35], v[70:71] op_sel_hi:[1,0]
	v_pk_add_f32 v[36:37], v[36:37], v[70:71] op_sel_hi:[1,0]
	v_lshlrev_b32_e32 v74, 16, v64
	v_and_b32_e32 v75, 0xffff0000, v64
	v_lshlrev_b32_e32 v64, 16, v65
	v_and_b32_e32 v65, 0xffff0000, v65
	v_pk_mul_f32 v[58:59], v[58:59], v[74:75]
	v_pk_mul_f32 v[60:61], v[60:61], v[64:65]
	v_cvt_pk_bf16_f32 v58, v58, v59
	v_cvt_pk_bf16_f32 v59, v60, v61
	global_store_dwordx2 v[62:63], v[58:59], off offset:1056
	v_mov_b32_e32 v58, v116
	v_mov_b32_e32 v59, v117
	v_lshlrev_b32_e32 v60, 16, v58
	v_and_b32_e32 v61, 0xffff0000, v58
	v_lshlrev_b32_e32 v58, 16, v59
	v_and_b32_e32 v59, 0xffff0000, v59
	v_pk_mul_f32 v[54:55], v[54:55], v[60:61]
	v_pk_mul_f32 v[56:57], v[56:57], v[58:59]
	v_cvt_pk_bf16_f32 v54, v54, v55
	v_cvt_pk_bf16_f32 v55, v56, v57
	global_store_dwordx2 v[62:63], v[54:55], off offset:1088
	v_mov_b32_e32 v54, v118
	v_mov_b32_e32 v55, v119
	v_lshlrev_b32_e32 v56, 16, v54
	v_and_b32_e32 v57, 0xffff0000, v54
	v_lshlrev_b32_e32 v54, 16, v55
	v_and_b32_e32 v55, 0xffff0000, v55
	v_pk_mul_f32 v[50:51], v[50:51], v[56:57]
	v_pk_mul_f32 v[52:53], v[52:53], v[54:55]
	v_cvt_pk_bf16_f32 v50, v50, v51
	v_cvt_pk_bf16_f32 v51, v52, v53
	global_store_dwordx2 v[62:63], v[50:51], off offset:1120
	v_mov_b32_e32 v50, v120
	v_mov_b32_e32 v51, v121
	v_lshlrev_b32_e32 v52, 16, v50
	v_and_b32_e32 v53, 0xffff0000, v50
	v_lshlrev_b32_e32 v50, 16, v51
	v_and_b32_e32 v51, 0xffff0000, v51
	v_pk_mul_f32 v[46:47], v[46:47], v[52:53]
	v_pk_mul_f32 v[48:49], v[48:49], v[50:51]
	v_cvt_pk_bf16_f32 v46, v46, v47
	v_cvt_pk_bf16_f32 v47, v48, v49
	global_store_dwordx2 v[62:63], v[46:47], off offset:1152
	v_mov_b32_e32 v46, v122
	v_mov_b32_e32 v47, v123
	v_lshlrev_b32_e32 v48, 16, v46
	v_and_b32_e32 v49, 0xffff0000, v46
	v_lshlrev_b32_e32 v46, 16, v47
	v_and_b32_e32 v47, 0xffff0000, v47
	v_pk_mul_f32 v[42:43], v[42:43], v[48:49]
	v_pk_mul_f32 v[44:45], v[44:45], v[46:47]
	v_cvt_pk_bf16_f32 v42, v42, v43
	v_cvt_pk_bf16_f32 v43, v44, v45
	global_store_dwordx2 v[62:63], v[42:43], off offset:1184
	v_mov_b32_e32 v42, v124
	v_mov_b32_e32 v43, v125
	v_lshlrev_b32_e32 v44, 16, v42
	v_and_b32_e32 v45, 0xffff0000, v42
	v_lshlrev_b32_e32 v42, 16, v43
	v_and_b32_e32 v43, 0xffff0000, v43
	v_pk_mul_f32 v[38:39], v[38:39], v[44:45]
	v_pk_mul_f32 v[40:41], v[40:41], v[42:43]
	v_cvt_pk_bf16_f32 v38, v38, v39
	v_cvt_pk_bf16_f32 v39, v40, v41
	global_store_dwordx2 v[62:63], v[38:39], off offset:1216
	v_mov_b32_e32 v38, v126
	v_mov_b32_e32 v39, v127
	v_lshlrev_b32_e32 v40, 16, v38
	v_and_b32_e32 v41, 0xffff0000, v38
	v_lshlrev_b32_e32 v38, 16, v39
	v_and_b32_e32 v39, 0xffff0000, v39
	v_pk_mul_f32 v[34:35], v[34:35], v[40:41]
	v_pk_mul_f32 v[36:37], v[36:37], v[38:39]
	v_cvt_pk_bf16_f32 v34, v34, v35
	v_cvt_pk_bf16_f32 v35, v36, v37
	v_or_b32_e32 v36, 16, v66
	v_ashrrev_i32_e32 v37, 31, v36
	v_lshlrev_b64 v[38:39], 11, v[36:37]
	v_lshl_add_u64 v[36:37], s[6:7], 0, v[38:39]
	global_store_dwordx2 v[62:63], v[34:35], off offset:1248
; __device__ __forceinline__ float lo_bf(unsigned u) { return __uint_as_float(u << 16); }
; __device__ __forceinline__ float hi_bf(unsigned u) { return __uint_as_float(u & 0xffff0000u); }
; __device__ __forceinline__ void cmlp_item(const Params& p, int j, int rt, int g, const u16* __restrict__ ZB, u16* sVT) {
;     ...
; #pragma unroll
;   for (int pb = 0; pb < 2; ++pb) {
;     const int pp = wave * 32 + pb * 16 + fr;
;     const float bias = p.cmlp_bs[(j * 4 + g) * 128 + pp];
; #pragma unroll
;     for (int db = 0; db < 8; ++db) {
;       const int d = db * 16 + fq * 4;
;       uint2 uu = *(const uint2*)(ZB + (size_t)(m0 + pp) * 1024 + g * 128 + d);
;       f32x4 r;
;       r[0] = lo_bf(uu.x) * (acc[pb][db][0] + bias);
;       r[1] = hi_bf(uu.x) * (acc[pb][db][1] + bias);
;       r[2] = lo_bf(uu.y) * (acc[pb][db][2] + bias);
;       r[3] = hi_bf(uu.y) * (acc[pb][db][3] + bias);
;       store4bf(p.XN + (size_t)(m0 + pp) * 1024 + 512 + g * 128 + d, r);
;     }
;   }
	v_lshl_add_u64 v[36:37], v[36:37], 0, v[0:1]
	v_mov_b32_e32 v34, v112
	v_mov_b32_e32 v40, v128
	v_mov_b32_e32 v41, v129
	v_pk_add_f32 v[30:31], v[30:31], v[34:35] op_sel_hi:[1,0]
	v_lshlrev_b32_e32 v42, 16, v40
	v_and_b32_e32 v43, 0xffff0000, v40
	v_pk_mul_f32 v[42:43], v[30:31], v[42:43]
	v_lshlrev_b32_e32 v30, 16, v41
	v_and_b32_e32 v31, 0xffff0000, v41
	v_pk_add_f32 v[32:33], v[32:33], v[34:35] op_sel_hi:[1,0]
	v_pk_add_f32 v[26:27], v[26:27], v[34:35] op_sel_hi:[1,0]
	v_pk_mul_f32 v[32:33], v[32:33], v[30:31]
	v_lshl_add_u64 v[30:31], s[42:43], 0, v[38:39]
	v_lshl_add_u64 v[30:31], v[30:31], 0, s[34:35]
	v_lshl_add_u64 v[30:31], v[30:31], 0, v[0:1]
	v_cvt_pk_bf16_f32 v38, v42, v43
	v_cvt_pk_bf16_f32 v39, v32, v33
	global_store_dwordx2 v[30:31], v[38:39], off offset:1024
	v_mov_b32_e32 v32, v130
	v_mov_b32_e32 v33, v131
	v_pk_add_f32 v[28:29], v[28:29], v[34:35] op_sel_hi:[1,0]
	v_pk_add_f32 v[22:23], v[22:23], v[34:35] op_sel_hi:[1,0]
	v_pk_add_f32 v[24:25], v[24:25], v[34:35] op_sel_hi:[1,0]
	v_pk_add_f32 v[18:19], v[18:19], v[34:35] op_sel_hi:[1,0]
	v_pk_add_f32 v[20:21], v[20:21], v[34:35] op_sel_hi:[1,0]
	v_pk_add_f32 v[14:15], v[14:15], v[34:35] op_sel_hi:[1,0]
	v_pk_add_f32 v[16:17], v[16:17], v[34:35] op_sel_hi:[1,0]
	v_pk_add_f32 v[10:11], v[10:11], v[34:35] op_sel_hi:[1,0]
	v_pk_add_f32 v[12:13], v[12:13], v[34:35] op_sel_hi:[1,0]
	v_pk_add_f32 v[6:7], v[6:7], v[34:35] op_sel_hi:[1,0]
	v_pk_add_f32 v[8:9], v[8:9], v[34:35] op_sel_hi:[1,0]
	v_pk_add_f32 v[2:3], v[2:3], v[34:35] op_sel_hi:[1,0]
	v_pk_add_f32 v[4:5], v[4:5], v[34:35] op_sel_hi:[1,0]
	v_lshlrev_b32_e32 v38, 16, v32
	v_and_b32_e32 v39, 0xffff0000, v32
	v_lshlrev_b32_e32 v32, 16, v33
	v_and_b32_e32 v33, 0xffff0000, v33
	v_pk_mul_f32 v[26:27], v[26:27], v[38:39]
	v_pk_mul_f32 v[28:29], v[28:29], v[32:33]
	v_cvt_pk_bf16_f32 v26, v26, v27
	v_cvt_pk_bf16_f32 v27, v28, v29
	global_store_dwordx2 v[30:31], v[26:27], off offset:1056
	v_mov_b32_e32 v26, v132
	v_mov_b32_e32 v27, v133
	v_lshlrev_b32_e32 v28, 16, v26
	v_and_b32_e32 v29, 0xffff0000, v26
	v_lshlrev_b32_e32 v26, 16, v27
	v_and_b32_e32 v27, 0xffff0000, v27
	v_pk_mul_f32 v[22:23], v[22:23], v[28:29]
	v_pk_mul_f32 v[24:25], v[24:25], v[26:27]
	v_cvt_pk_bf16_f32 v22, v22, v23
	v_cvt_pk_bf16_f32 v23, v24, v25
	global_store_dwordx2 v[30:31], v[22:23], off offset:1088
	v_mov_b32_e32 v22, v134
	v_mov_b32_e32 v23, v135
	v_lshlrev_b32_e32 v24, 16, v22
	v_and_b32_e32 v25, 0xffff0000, v22
	v_lshlrev_b32_e32 v22, 16, v23
	v_and_b32_e32 v23, 0xffff0000, v23
	v_pk_mul_f32 v[18:19], v[18:19], v[24:25]
	v_pk_mul_f32 v[20:21], v[20:21], v[22:23]
	v_cvt_pk_bf16_f32 v18, v18, v19
	v_cvt_pk_bf16_f32 v19, v20, v21
	global_store_dwordx2 v[30:31], v[18:19], off offset:1120
	v_mov_b32_e32 v18, v136
	v_mov_b32_e32 v19, v137
	v_lshlrev_b32_e32 v20, 16, v18
	v_and_b32_e32 v21, 0xffff0000, v18
	v_lshlrev_b32_e32 v18, 16, v19
	v_and_b32_e32 v19, 0xffff0000, v19
	v_pk_mul_f32 v[14:15], v[14:15], v[20:21]
	v_pk_mul_f32 v[16:17], v[16:17], v[18:19]
	v_cvt_pk_bf16_f32 v14, v14, v15
	v_cvt_pk_bf16_f32 v15, v16, v17
	global_store_dwordx2 v[30:31], v[14:15], off offset:1152
	v_mov_b32_e32 v14, v138
	v_mov_b32_e32 v15, v139
	v_lshlrev_b32_e32 v16, 16, v14
	v_and_b32_e32 v17, 0xffff0000, v14
	v_lshlrev_b32_e32 v14, 16, v15
	v_and_b32_e32 v15, 0xffff0000, v15
	v_pk_mul_f32 v[10:11], v[10:11], v[16:17]
	v_pk_mul_f32 v[12:13], v[12:13], v[14:15]
	v_cvt_pk_bf16_f32 v10, v10, v11
	v_cvt_pk_bf16_f32 v11, v12, v13
	global_store_dwordx2 v[30:31], v[10:11], off offset:1184
	v_mov_b32_e32 v10, v140
	v_mov_b32_e32 v11, v141
	v_lshlrev_b32_e32 v12, 16, v10
	v_and_b32_e32 v13, 0xffff0000, v10
	v_lshlrev_b32_e32 v10, 16, v11
	v_and_b32_e32 v11, 0xffff0000, v11
	v_pk_mul_f32 v[6:7], v[6:7], v[12:13]
	v_pk_mul_f32 v[8:9], v[8:9], v[10:11]
	v_cvt_pk_bf16_f32 v6, v6, v7
	v_cvt_pk_bf16_f32 v7, v8, v9
	global_store_dwordx2 v[30:31], v[6:7], off offset:1216
	v_mov_b32_e32 v6, v142
	v_mov_b32_e32 v7, v143
	v_lshlrev_b32_e32 v8, 16, v6
	v_and_b32_e32 v9, 0xffff0000, v6
	v_lshlrev_b32_e32 v6, 16, v7
	v_and_b32_e32 v7, 0xffff0000, v7
	v_pk_mul_f32 v[2:3], v[2:3], v[8:9]
	v_pk_mul_f32 v[4:5], v[4:5], v[6:7]
	v_cvt_pk_bf16_f32 v2, v2, v3
	v_cvt_pk_bf16_f32 v3, v4, v5
	global_store_dwordx2 v[30:31], v[2:3], off offset:1248
	s_cbranch_scc0 .LBB0_1553
	v_readlane_b32 s44, v255, 21
	s_branch .LBB0_1524
